# v42 + K-loop load-phase cleanup: merged vmcnt/lgkmcnt waits into one s_waitcnt, address VALU supplies the m0->LDS-DMA wait state instead of s_nop 0 (46 nops removed)
# baseline (speedup 1.0000x reference)
; #define PG8_STAGE(bufoff, gbase, voff) do { _Pragma("unroll") for (int _i = 0; _i < 2; ++_i) \
;         __builtin_amdgcn_global_load_lds((const unsigned*)((const char*)(gbase) + (voff)[_i]), (PG8_LAS unsigned*)(lds + (bufoff) + ldsw + _i * 8192), 16, 0, 0); } while (0)
; #define PG8_WAIT_V(n) asm volatile("s_waitcnt vmcnt(" #n ")" ::: "memory")
; #define PG8_WAIT_L(n) asm volatile("s_waitcnt lgkmcnt(" #n ")" ::: "memory")
; #define PG8_BAR __builtin_amdgcn_s_barrier()
; #define PG8_SCHED __builtin_amdgcn_sched_barrier(0)
;     ...
;             const bool last = (t == nt - 2);
;             const char* a1 = cA + (size_t)(t + 1) * kstep;
;             const char* a2 = last ? nA : cA + (size_t)(t + 2) * kstep; const char* b2 = last ? nB : cB + (size_t)(t + 2) * kstep;
;             const char* a3 = a2 + kstep; const char* b3 = b2 + kstep;
;             if (last && has_next) S.a_ready(nxt);
;             if (last) E.pre(pre, cur, wr, fr);
;             if constexpr (MIDK > 0) { if (t == MIDK / BK) E.mid(acc, cur, wr, wc, fr, fq); }
;             if constexpr (SP2) {
;             PG8_LDB(B0, 0, 0); PG8_LDB(B1, 0, 1); PG8_SCHED; PG8_LDA(At, 0, 0); PG8_STAGE(PG8_SA(1, 1), a1 + hstep, voffA);
;             PG8_WAIT_V(8); PG8_WAIT_L(0); PG8_BAR; PG8_MMA(0, 0, At, B0); PG8_MMA(0, 1, At, B1); PG8_BAR; PG8_SCHED;
;             PG8_LDA(At, 0, 1); PG8_STAGE(PG8_SB(0, 0), b2, voffB); PG8_STAGE(PG8_SB(0, 1), b2 + hstep, voffB); PG8_STAGE(PG8_SA(0, 0), a2, voffA);
;             PG8_WAIT_V(8); PG8_WAIT_L(0); PG8_BAR; PG8_MMA(1, 0, At, B0); PG8_MMA(1, 1, At, B1); PG8_BAR; PG8_SCHED;
.LBB0_248:
	v_add_u32_e32 v155, s68, v149
	ds_read_b128 v[166:169], v155
	ds_read_b128 v[170:173], v155 offset:1024
	ds_read_b128 v[174:177], v155 offset:2048
	ds_read_b128 v[178:181], v155 offset:3072
	v_add_u32_e32 v155, s69, v149
	ds_read_b128 v[182:185], v155
	ds_read_b128 v[186:189], v155 offset:1024
	ds_read_b128 v[190:193], v155 offset:2048
	ds_read_b128 v[194:197], v155 offset:3072
	s_add_u32 s33, s50, 0xfffc0080
	s_addc_u32 s54, s51, -1
	s_and_b64 s[52:53], s[52:53], exec
	s_cselect_b32 s55, s25, s54
	s_cselect_b32 s54, s34, s33
	s_cselect_b32 s53, s21, s73
	s_cselect_b32 s52, s35, s72
	v_lshl_add_u64 v[210:211], s[50:51], 0, v[138:139]
	s_add_i32 m0, s59, 0xc000
	ds_read_b128 v[198:201], v153
	ds_read_b128 v[202:205], v153 offset:1024
	ds_read_b128 v[206:209], v153 offset:2048
	ds_read_b128 v[214:217], v153 offset:3072
	ds_read_b128 v[218:221], v153 offset:4096
	ds_read_b128 v[222:225], v153 offset:5120
	ds_read_b128 v[226:229], v153 offset:6144
	ds_read_b128 v[230:233], v153 offset:7168
	global_load_lds_dwordx4 v[210:211], off
	s_add_i32 m0, s59, 0xe000
	v_lshl_add_u64 v[210:211], s[50:51], 0, v[140:141]
	global_load_lds_dwordx4 v[210:211], off
	s_waitcnt vmcnt(8) lgkmcnt(0)
	s_barrier
	v_mfma_i32_16x16x64_i8 v[124:127], v[166:169], v[198:201], v[124:127]
	v_mfma_i32_16x16x64_i8 v[124:127], v[170:173], v[202:205], v[124:127]
	v_mfma_i32_16x16x64_i8 v[116:119], v[174:177], v[198:201], v[116:119]
	v_mfma_i32_16x16x64_i8 v[116:119], v[178:181], v[202:205], v[116:119]
	v_mfma_i32_16x16x64_i8 v[108:111], v[166:169], v[206:209], v[108:111]
	v_mfma_i32_16x16x64_i8 v[108:111], v[170:173], v[214:217], v[108:111]
	v_mfma_i32_16x16x64_i8 v[100:103], v[174:177], v[206:209], v[100:103]
	v_mfma_i32_16x16x64_i8 v[100:103], v[178:181], v[214:217], v[100:103]
	v_mfma_i32_16x16x64_i8 v[92:95], v[166:169], v[218:221], v[92:95]
	v_mfma_i32_16x16x64_i8 v[92:95], v[170:173], v[222:225], v[92:95]
	v_mfma_i32_16x16x64_i8 v[84:87], v[174:177], v[218:221], v[84:87]
	v_mfma_i32_16x16x64_i8 v[84:87], v[178:181], v[222:225], v[84:87]
	v_mfma_i32_16x16x64_i8 v[76:79], v[166:169], v[226:229], v[76:79]
	v_mfma_i32_16x16x64_i8 v[76:79], v[170:173], v[230:233], v[76:79]
	v_mfma_i32_16x16x64_i8 v[68:71], v[174:177], v[226:229], v[68:71]
	v_mfma_i32_16x16x64_i8 v[68:71], v[178:181], v[230:233], v[68:71]
	v_mfma_i32_16x16x64_i8 v[120:123], v[182:185], v[198:201], v[120:123]
	v_mfma_i32_16x16x64_i8 v[120:123], v[186:189], v[202:205], v[120:123]
	v_mfma_i32_16x16x64_i8 v[112:115], v[190:193], v[198:201], v[112:115]
	v_mfma_i32_16x16x64_i8 v[112:115], v[194:197], v[202:205], v[112:115]
	v_mfma_i32_16x16x64_i8 v[104:107], v[182:185], v[206:209], v[104:107]
	v_mfma_i32_16x16x64_i8 v[104:107], v[186:189], v[214:217], v[104:107]
	v_mfma_i32_16x16x64_i8 v[96:99], v[190:193], v[206:209], v[96:99]
	v_mfma_i32_16x16x64_i8 v[96:99], v[194:197], v[214:217], v[96:99]
	v_mfma_i32_16x16x64_i8 v[88:91], v[182:185], v[218:221], v[88:91]
	v_mfma_i32_16x16x64_i8 v[88:91], v[186:189], v[222:225], v[88:91]
	v_mfma_i32_16x16x64_i8 v[80:83], v[190:193], v[218:221], v[80:83]
	v_mfma_i32_16x16x64_i8 v[80:83], v[194:197], v[222:225], v[80:83]
	v_mfma_i32_16x16x64_i8 v[72:75], v[182:185], v[226:229], v[72:75]
	v_mfma_i32_16x16x64_i8 v[72:75], v[186:189], v[230:233], v[72:75]
	v_mfma_i32_16x16x64_i8 v[64:67], v[190:193], v[226:229], v[64:67]
	v_mfma_i32_16x16x64_i8 v[64:67], v[194:197], v[230:233], v[64:67]
	s_barrier
	s_add_i32 s33, s68, s56
	v_lshl_add_u64 v[210:211], s[52:53], 0, v[132:133]
	s_mov_b32 m0, s33
	ds_read_b128 v[198:201], v153 offset:16384
	ds_read_b128 v[202:205], v153 offset:17408
	ds_read_b128 v[206:209], v153 offset:18432
	ds_read_b128 v[214:217], v153 offset:19456
	ds_read_b128 v[218:221], v153 offset:20480
	ds_read_b128 v[222:225], v153 offset:21504
	ds_read_b128 v[226:229], v153 offset:22528
	ds_read_b128 v[230:233], v153 offset:23552
	global_load_lds_dwordx4 v[210:211], off
	s_add_i32 m0, s33, 0x2000
	s_add_u32 s76, s52, 0x40000
	v_lshl_add_u64 v[234:235], s[52:53], 0, v[128:129]
	s_addc_u32 s77, s53, 0
	s_add_i32 s33, s69, s56
	global_load_lds_dwordx4 v[234:235], off
	v_lshl_add_u64 v[236:237], s[76:77], 0, v[132:133]
	s_mov_b32 m0, s33
	v_lshl_add_u64 v[238:239], s[54:55], 0, v[130:131]
	global_load_lds_dwordx4 v[236:237], off
	s_add_i32 m0, s33, 0x2000
	v_lshl_add_u64 v[236:237], s[76:77], 0, v[128:129]
	global_load_lds_dwordx4 v[236:237], off
	s_mov_b32 m0, s59
	v_lshl_add_u64 v[236:237], s[54:55], 0, v[134:135]
	global_load_lds_dwordx4 v[236:237], off
	s_mov_b32 m0, s60
	s_nop 0
	global_load_lds_dwordx4 v[238:239], off
	s_waitcnt vmcnt(8) lgkmcnt(0)
	s_barrier
; #define PG8_STAGE(bufoff, gbase, voff) do { _Pragma("unroll") for (int _i = 0; _i < 2; ++_i) \
;         __builtin_amdgcn_global_load_lds((const unsigned*)((const char*)(gbase) + (voff)[_i]), (PG8_LAS unsigned*)(lds + (bufoff) + ldsw + _i * 8192), 16, 0, 0); } while (0)
; #define PG8_WAIT_V(n) asm volatile("s_waitcnt vmcnt(" #n ")" ::: "memory")
; #define PG8_WAIT_L(n) asm volatile("s_waitcnt lgkmcnt(" #n ")" ::: "memory")
; #define PG8_BAR __builtin_amdgcn_s_barrier()
; #define PG8_SCHED __builtin_amdgcn_sched_barrier(0)
;     ...
;             PG8_WAIT_V(8); PG8_WAIT_L(0); PG8_BAR; PG8_MMA(1, 0, At, B0); PG8_MMA(1, 1, At, B1); PG8_BAR; PG8_SCHED;
;             PG8_LDB(B0, 1, 0); PG8_LDB(B1, 1, 1); PG8_SCHED; PG8_LDA(At, 1, 0); PG8_STAGE(PG8_SA(0, 1), a2 + hstep, voffA);
;             PG8_WAIT_V(8); PG8_WAIT_L(0); PG8_BAR; PG8_MMA(0, 0, At, B0); PG8_MMA(0, 1, At, B1); PG8_BAR; PG8_SCHED;
	v_mfma_i32_16x16x64_i8 v[60:63], v[166:169], v[198:201], v[60:63]
	v_mfma_i32_16x16x64_i8 v[60:63], v[170:173], v[202:205], v[60:63]
	v_mfma_i32_16x16x64_i8 v[52:55], v[174:177], v[198:201], v[52:55]
	v_mfma_i32_16x16x64_i8 v[52:55], v[178:181], v[202:205], v[52:55]
	v_mfma_i32_16x16x64_i8 v[44:47], v[166:169], v[206:209], v[44:47]
	v_mfma_i32_16x16x64_i8 v[44:47], v[170:173], v[214:217], v[44:47]
	v_mfma_i32_16x16x64_i8 v[36:39], v[174:177], v[206:209], v[36:39]
	v_mfma_i32_16x16x64_i8 v[36:39], v[178:181], v[214:217], v[36:39]
	v_mfma_i32_16x16x64_i8 v[28:31], v[166:169], v[218:221], v[28:31]
	v_mfma_i32_16x16x64_i8 v[28:31], v[170:173], v[222:225], v[28:31]
	v_mfma_i32_16x16x64_i8 v[20:23], v[174:177], v[218:221], v[20:23]
	v_mfma_i32_16x16x64_i8 v[20:23], v[178:181], v[222:225], v[20:23]
	v_mfma_i32_16x16x64_i8 v[12:15], v[166:169], v[226:229], v[12:15]
	v_mfma_i32_16x16x64_i8 v[12:15], v[170:173], v[230:233], v[12:15]
	v_mfma_i32_16x16x64_i8 v[4:7], v[174:177], v[226:229], v[4:7]
	v_mfma_i32_16x16x64_i8 v[4:7], v[178:181], v[230:233], v[4:7]
	v_mfma_i32_16x16x64_i8 v[56:59], v[182:185], v[198:201], v[56:59]
	v_mfma_i32_16x16x64_i8 v[56:59], v[186:189], v[202:205], v[56:59]
	v_mfma_i32_16x16x64_i8 v[48:51], v[190:193], v[198:201], v[48:51]
	v_mfma_i32_16x16x64_i8 v[48:51], v[194:197], v[202:205], v[48:51]
	v_mfma_i32_16x16x64_i8 v[40:43], v[182:185], v[206:209], v[40:43]
	v_mfma_i32_16x16x64_i8 v[40:43], v[186:189], v[214:217], v[40:43]
	v_mfma_i32_16x16x64_i8 v[32:35], v[190:193], v[206:209], v[32:35]
	v_mfma_i32_16x16x64_i8 v[32:35], v[194:197], v[214:217], v[32:35]
	v_mfma_i32_16x16x64_i8 v[24:27], v[182:185], v[218:221], v[24:27]
	v_mfma_i32_16x16x64_i8 v[24:27], v[186:189], v[222:225], v[24:27]
	v_mfma_i32_16x16x64_i8 v[16:19], v[190:193], v[218:221], v[16:19]
	v_mfma_i32_16x16x64_i8 v[16:19], v[194:197], v[222:225], v[16:19]
	v_mfma_i32_16x16x64_i8 v[8:11], v[182:185], v[226:229], v[8:11]
	v_mfma_i32_16x16x64_i8 v[8:11], v[186:189], v[230:233], v[8:11]
	v_mfma_i32_16x16x64_i8 v[0:3], v[190:193], v[226:229], v[0:3]
	v_mfma_i32_16x16x64_i8 v[0:3], v[194:197], v[230:233], v[0:3]
	s_barrier
	s_add_i32 s33, 0, 0x18000
	v_add_u32_e32 v155, s33, v149
	s_add_i32 s75, 0, 0x1c000
	ds_read_b128 v[166:169], v155
	ds_read_b128 v[170:173], v155 offset:1024
	ds_read_b128 v[174:177], v155 offset:2048
	ds_read_b128 v[178:181], v155 offset:3072
	v_add_u32_e32 v155, s75, v149
	ds_read_b128 v[182:185], v155
	ds_read_b128 v[186:189], v155 offset:1024
	ds_read_b128 v[190:193], v155 offset:2048
	ds_read_b128 v[194:197], v155 offset:3072
	s_add_u32 s54, s54, 0x40000
	s_addc_u32 s55, s55, 0
	s_mov_b32 m0, s61
	v_lshl_add_u64 v[240:241], s[54:55], 0, v[134:135]
	ds_read_b128 v[198:201], v153 offset:32768
	ds_read_b128 v[202:205], v153 offset:33792
	ds_read_b128 v[206:209], v153 offset:34816
	ds_read_b128 v[214:217], v153 offset:35840
	ds_read_b128 v[218:221], v153 offset:36864
	ds_read_b128 v[222:225], v153 offset:37888
	ds_read_b128 v[226:229], v153 offset:38912
	ds_read_b128 v[230:233], v153 offset:39936
	global_load_lds_dwordx4 v[240:241], off
	s_mov_b32 m0, s62
	v_lshl_add_u64 v[240:241], s[54:55], 0, v[130:131]
	global_load_lds_dwordx4 v[240:241], off
	s_waitcnt vmcnt(8) lgkmcnt(0)
	s_barrier
	v_mfma_i32_16x16x64_i8 v[124:127], v[166:169], v[198:201], v[124:127]
	v_mfma_i32_16x16x64_i8 v[124:127], v[170:173], v[202:205], v[124:127]
	v_mfma_i32_16x16x64_i8 v[116:119], v[174:177], v[198:201], v[116:119]
	v_mfma_i32_16x16x64_i8 v[116:119], v[178:181], v[202:205], v[116:119]
	v_mfma_i32_16x16x64_i8 v[108:111], v[166:169], v[206:209], v[108:111]
	v_mfma_i32_16x16x64_i8 v[108:111], v[170:173], v[214:217], v[108:111]
	v_mfma_i32_16x16x64_i8 v[100:103], v[174:177], v[206:209], v[100:103]
	v_mfma_i32_16x16x64_i8 v[100:103], v[178:181], v[214:217], v[100:103]
	v_mfma_i32_16x16x64_i8 v[92:95], v[166:169], v[218:221], v[92:95]
	v_mfma_i32_16x16x64_i8 v[92:95], v[170:173], v[222:225], v[92:95]
	v_mfma_i32_16x16x64_i8 v[84:87], v[174:177], v[218:221], v[84:87]
	v_mfma_i32_16x16x64_i8 v[84:87], v[178:181], v[222:225], v[84:87]
	v_mfma_i32_16x16x64_i8 v[76:79], v[166:169], v[226:229], v[76:79]
	v_mfma_i32_16x16x64_i8 v[76:79], v[170:173], v[230:233], v[76:79]
	v_mfma_i32_16x16x64_i8 v[68:71], v[174:177], v[226:229], v[68:71]
	v_mfma_i32_16x16x64_i8 v[68:71], v[178:181], v[230:233], v[68:71]
	v_mfma_i32_16x16x64_i8 v[120:123], v[182:185], v[198:201], v[120:123]
	v_mfma_i32_16x16x64_i8 v[120:123], v[186:189], v[202:205], v[120:123]
	v_mfma_i32_16x16x64_i8 v[112:115], v[190:193], v[198:201], v[112:115]
	v_mfma_i32_16x16x64_i8 v[112:115], v[194:197], v[202:205], v[112:115]
	v_mfma_i32_16x16x64_i8 v[104:107], v[182:185], v[206:209], v[104:107]
	v_mfma_i32_16x16x64_i8 v[104:107], v[186:189], v[214:217], v[104:107]
	v_mfma_i32_16x16x64_i8 v[96:99], v[190:193], v[206:209], v[96:99]
	v_mfma_i32_16x16x64_i8 v[96:99], v[194:197], v[214:217], v[96:99]
	v_mfma_i32_16x16x64_i8 v[88:91], v[182:185], v[218:221], v[88:91]
	v_mfma_i32_16x16x64_i8 v[88:91], v[186:189], v[222:225], v[88:91]
	v_mfma_i32_16x16x64_i8 v[80:83], v[190:193], v[218:221], v[80:83]
	v_mfma_i32_16x16x64_i8 v[80:83], v[194:197], v[222:225], v[80:83]
	v_mfma_i32_16x16x64_i8 v[72:75], v[182:185], v[226:229], v[72:75]
	v_mfma_i32_16x16x64_i8 v[72:75], v[186:189], v[230:233], v[72:75]
	v_mfma_i32_16x16x64_i8 v[64:67], v[190:193], v[226:229], v[64:67]
	v_mfma_i32_16x16x64_i8 v[64:67], v[194:197], v[230:233], v[64:67]
	s_barrier
; #define PG8_STAGE(bufoff, gbase, voff) do { _Pragma("unroll") for (int _i = 0; _i < 2; ++_i) \
;         __builtin_amdgcn_global_load_lds((const unsigned*)((const char*)(gbase) + (voff)[_i]), (PG8_LAS unsigned*)(lds + (bufoff) + ldsw + _i * 8192), 16, 0, 0); } while (0)
; #define PG8_WAIT_V(n) asm volatile("s_waitcnt vmcnt(" #n ")" ::: "memory")
; #define PG8_WAIT_L(n) asm volatile("s_waitcnt lgkmcnt(" #n ")" ::: "memory")
; #define PG8_BAR __builtin_amdgcn_s_barrier()
; #define PG8_SCHED __builtin_amdgcn_sched_barrier(0)
;     ...
;             PG8_LDA(At, 1, 1); PG8_STAGE(PG8_SB(1, 0), b3, voffB); PG8_STAGE(PG8_SB(1, 1), b3 + hstep, voffB); PG8_STAGE(PG8_SA(1, 0), a3, voffA);
;             PG8_WAIT_V(8); PG8_WAIT_L(0); PG8_BAR; PG8_MMA(1, 0, At, B0); PG8_MMA(1, 1, At, B1); PG8_BAR; PG8_SCHED;
	s_add_i32 s33, s33, s56
	v_lshl_add_u64 v[210:211], v[210:211], 0, s[10:11]
	s_mov_b32 m0, s33
	ds_read_b128 v[198:201], v153 offset:49152
	ds_read_b128 v[202:205], v153 offset:50176
	ds_read_b128 v[206:209], v153 offset:51200
	ds_read_b128 v[214:217], v153 offset:52224
	ds_read_b128 v[218:221], v153 offset:53248
	ds_read_b128 v[222:225], v153 offset:54272
	ds_read_b128 v[226:229], v153 offset:55296
	ds_read_b128 v[230:233], v153 offset:56320
	global_load_lds_dwordx4 v[210:211], off
	s_add_i32 m0, s33, 0x2000
	s_add_u32 s52, s52, 0x40080
	v_lshl_add_u64 v[210:211], v[234:235], 0, s[10:11]
	s_addc_u32 s53, s53, 0
	s_add_i32 s33, s75, s56
	global_load_lds_dwordx4 v[210:211], off
	s_mov_b32 m0, s33
	v_lshl_add_u64 v[210:211], s[52:53], 0, v[132:133]
	global_load_lds_dwordx4 v[210:211], off
	s_add_i32 m0, s33, 0x2000
	v_lshl_add_u64 v[210:211], s[52:53], 0, v[128:129]
	global_load_lds_dwordx4 v[210:211], off
	s_mov_b32 m0, s64
	v_lshl_add_u64 v[210:211], v[236:237], 0, s[10:11]
	global_load_lds_dwordx4 v[210:211], off
	s_mov_b32 m0, s65
	v_lshl_add_u64 v[210:211], v[238:239], 0, s[10:11]
	global_load_lds_dwordx4 v[210:211], off
	s_waitcnt vmcnt(8) lgkmcnt(0)
	s_barrier
	v_mfma_i32_16x16x64_i8 v[60:63], v[166:169], v[198:201], v[60:63]
	v_mfma_i32_16x16x64_i8 v[60:63], v[170:173], v[202:205], v[60:63]
	v_mfma_i32_16x16x64_i8 v[52:55], v[174:177], v[198:201], v[52:55]
	v_mfma_i32_16x16x64_i8 v[52:55], v[178:181], v[202:205], v[52:55]
	v_mfma_i32_16x16x64_i8 v[44:47], v[166:169], v[206:209], v[44:47]
	v_mfma_i32_16x16x64_i8 v[44:47], v[170:173], v[214:217], v[44:47]
	v_mfma_i32_16x16x64_i8 v[36:39], v[174:177], v[206:209], v[36:39]
	v_mfma_i32_16x16x64_i8 v[36:39], v[178:181], v[214:217], v[36:39]
	v_mfma_i32_16x16x64_i8 v[28:31], v[166:169], v[218:221], v[28:31]
	v_mfma_i32_16x16x64_i8 v[28:31], v[170:173], v[222:225], v[28:31]
	v_mfma_i32_16x16x64_i8 v[20:23], v[174:177], v[218:221], v[20:23]
	v_mfma_i32_16x16x64_i8 v[20:23], v[178:181], v[222:225], v[20:23]
	v_mfma_i32_16x16x64_i8 v[12:15], v[166:169], v[226:229], v[12:15]
	v_mfma_i32_16x16x64_i8 v[12:15], v[170:173], v[230:233], v[12:15]
	v_mfma_i32_16x16x64_i8 v[4:7], v[174:177], v[226:229], v[4:7]
	v_mfma_i32_16x16x64_i8 v[4:7], v[178:181], v[230:233], v[4:7]
	v_mfma_i32_16x16x64_i8 v[56:59], v[182:185], v[198:201], v[56:59]
	v_mfma_i32_16x16x64_i8 v[56:59], v[186:189], v[202:205], v[56:59]
	v_mfma_i32_16x16x64_i8 v[48:51], v[190:193], v[198:201], v[48:51]
	v_mfma_i32_16x16x64_i8 v[48:51], v[194:197], v[202:205], v[48:51]
	v_mfma_i32_16x16x64_i8 v[40:43], v[182:185], v[206:209], v[40:43]
	v_mfma_i32_16x16x64_i8 v[40:43], v[186:189], v[214:217], v[40:43]
	v_mfma_i32_16x16x64_i8 v[32:35], v[190:193], v[206:209], v[32:35]
	v_mfma_i32_16x16x64_i8 v[32:35], v[194:197], v[214:217], v[32:35]
	v_mfma_i32_16x16x64_i8 v[24:27], v[182:185], v[218:221], v[24:27]
	v_mfma_i32_16x16x64_i8 v[24:27], v[186:189], v[222:225], v[24:27]
	v_mfma_i32_16x16x64_i8 v[16:19], v[190:193], v[218:221], v[16:19]
	v_mfma_i32_16x16x64_i8 v[16:19], v[194:197], v[222:225], v[16:19]
	v_mfma_i32_16x16x64_i8 v[8:11], v[182:185], v[226:229], v[8:11]
	v_mfma_i32_16x16x64_i8 v[8:11], v[186:189], v[230:233], v[8:11]
	v_mfma_i32_16x16x64_i8 v[0:3], v[190:193], v[226:229], v[0:3]
	v_mfma_i32_16x16x64_i8 v[0:3], v[194:197], v[230:233], v[0:3]
	s_barrier
	s_add_i32 s74, s74, 2
	s_add_u32 s50, s50, 0x100
	s_addc_u32 s51, s51, 0
	s_add_u32 s72, s72, 0x100
	s_addc_u32 s73, s73, 0
	s_cmp_gt_u32 s74, 13
	s_cbranch_scc1 .LBB0_251

; #define PG8_STAGE(bufoff, gbase, voff) do { _Pragma("unroll") for (int _i = 0; _i < 2; ++_i) \
;         __builtin_amdgcn_global_load_lds((const unsigned*)((const char*)(gbase) + (voff)[_i]), (PG8_LAS unsigned*)(lds + (bufoff) + ldsw + _i * 8192), 16, 0, 0); } while (0)
; #define PG8_WAIT_V(n) asm volatile("s_waitcnt vmcnt(" #n ")" ::: "memory")
; #define PG8_WAIT_L(n) asm volatile("s_waitcnt lgkmcnt(" #n ")" ::: "memory")
; #define PG8_BAR __builtin_amdgcn_s_barrier()
; #define PG8_SCHED __builtin_amdgcn_sched_barrier(0)
;     ...
;             const bool last = (t == nt - 2);
;             const char* a1 = cA + (size_t)(t + 1) * kstep;
;             const char* a2 = last ? nA : cA + (size_t)(t + 2) * kstep; const char* b2 = last ? nB : cB + (size_t)(t + 2) * kstep;
;             const char* a3 = a2 + kstep; const char* b3 = b2 + kstep;
;             if (last && has_next) S.a_ready(nxt);
;             if (last) E.pre(pre, cur, wr, fr);
;             if constexpr (MIDK > 0) { if (t == MIDK / BK) E.mid(acc, cur, wr, wc, fr, fq); }
;             if constexpr (SP2) {
;             PG8_LDB(B0, 0, 0); PG8_LDB(B1, 0, 1); PG8_SCHED; PG8_LDA(At, 0, 0); PG8_STAGE(PG8_SA(1, 1), a1 + hstep, voffA);
;             PG8_WAIT_V(8); PG8_WAIT_L(0); PG8_BAR; PG8_MMA(0, 0, At, B0); PG8_MMA(0, 1, At, B1); PG8_BAR; PG8_SCHED;
;             PG8_LDA(At, 0, 1); PG8_STAGE(PG8_SB(0, 0), b2, voffB); PG8_STAGE(PG8_SB(0, 1), b2 + hstep, voffB); PG8_STAGE(PG8_SA(0, 0), a2, voffA);
;             PG8_WAIT_V(8); PG8_WAIT_L(0); PG8_BAR; PG8_MMA(1, 0, At, B0); PG8_MMA(1, 1, At, B1); PG8_BAR; PG8_SCHED;
.LBB0_335:
	ds_read_b128 v[128:131], v191
	ds_read_b128 v[132:135], v191 offset:1024
	ds_read_b128 v[136:139], v191 offset:2048
	ds_read_b128 v[140:143], v191 offset:3072
	ds_read_b128 v[144:147], v192
	ds_read_b128 v[148:151], v192 offset:1024
	ds_read_b128 v[168:171], v192 offset:2048
	ds_read_b128 v[172:175], v192 offset:3072
	s_add_u32 s33, s50, 0xffea0080
	s_addc_u32 s52, s51, -1
	s_cmpk_eq_i32 s72, 0x54
	s_cselect_b32 s55, s1, s52
	s_cselect_b32 s54, s0, s33
	s_cselect_b32 s53, s49, s35
	s_cselect_b32 s52, s48, s34
	v_lshl_add_u64 v[218:219], s[50:51], 0, v[160:161]
	s_add_i32 m0, s56, 0xc000
	ds_read_b128 v[176:179], v193
	ds_read_b128 v[180:183], v193 offset:1024
	ds_read_b128 v[184:187], v193 offset:2048
	ds_read_b128 v[196:199], v193 offset:3072
	ds_read_b128 v[200:203], v193 offset:4096
	ds_read_b128 v[204:207], v193 offset:5120
	ds_read_b128 v[208:211], v193 offset:6144
	ds_read_b128 v[214:217], v193 offset:7168
	global_load_lds_dwordx4 v[218:219], off
	s_add_i32 m0, s56, 0xe000
	v_lshl_add_u64 v[218:219], s[50:51], 0, v[162:163]
	global_load_lds_dwordx4 v[218:219], off
	s_waitcnt vmcnt(8) lgkmcnt(0)
	s_barrier
	v_mfma_f32_16x16x32_bf16 v[124:127], v[128:131], v[176:179], v[124:127]
	v_mfma_f32_16x16x32_bf16 v[124:127], v[132:135], v[180:183], v[124:127]
	v_mfma_f32_16x16x32_bf16 v[120:123], v[136:139], v[176:179], v[120:123]
	v_mfma_f32_16x16x32_bf16 v[120:123], v[140:143], v[180:183], v[120:123]
	v_mfma_f32_16x16x32_bf16 v[108:111], v[128:131], v[184:187], v[108:111]
	v_mfma_f32_16x16x32_bf16 v[108:111], v[132:135], v[196:199], v[108:111]
	v_mfma_f32_16x16x32_bf16 v[104:107], v[136:139], v[184:187], v[104:107]
	v_mfma_f32_16x16x32_bf16 v[104:107], v[140:143], v[196:199], v[104:107]
	v_mfma_f32_16x16x32_bf16 v[92:95], v[128:131], v[200:203], v[92:95]
	v_mfma_f32_16x16x32_bf16 v[92:95], v[132:135], v[204:207], v[92:95]
	v_mfma_f32_16x16x32_bf16 v[88:91], v[136:139], v[200:203], v[88:91]
	v_mfma_f32_16x16x32_bf16 v[88:91], v[140:143], v[204:207], v[88:91]
	v_mfma_f32_16x16x32_bf16 v[76:79], v[128:131], v[208:211], v[76:79]
	v_mfma_f32_16x16x32_bf16 v[76:79], v[132:135], v[214:217], v[76:79]
	v_mfma_f32_16x16x32_bf16 v[72:75], v[136:139], v[208:211], v[72:75]
	v_mfma_f32_16x16x32_bf16 v[72:75], v[140:143], v[214:217], v[72:75]
	v_mfma_f32_16x16x32_bf16 v[116:119], v[144:147], v[176:179], v[116:119]
	v_mfma_f32_16x16x32_bf16 v[116:119], v[148:151], v[180:183], v[116:119]
	v_mfma_f32_16x16x32_bf16 v[112:115], v[168:171], v[176:179], v[112:115]
	v_mfma_f32_16x16x32_bf16 v[112:115], v[172:175], v[180:183], v[112:115]
	v_mfma_f32_16x16x32_bf16 v[100:103], v[144:147], v[184:187], v[100:103]
	v_mfma_f32_16x16x32_bf16 v[100:103], v[148:151], v[196:199], v[100:103]
	v_mfma_f32_16x16x32_bf16 v[96:99], v[168:171], v[184:187], v[96:99]
	v_mfma_f32_16x16x32_bf16 v[96:99], v[172:175], v[196:199], v[96:99]
	v_mfma_f32_16x16x32_bf16 v[84:87], v[144:147], v[200:203], v[84:87]
	v_mfma_f32_16x16x32_bf16 v[84:87], v[148:151], v[204:207], v[84:87]
	v_mfma_f32_16x16x32_bf16 v[80:83], v[168:171], v[200:203], v[80:83]
	v_mfma_f32_16x16x32_bf16 v[80:83], v[172:175], v[204:207], v[80:83]
	v_mfma_f32_16x16x32_bf16 v[68:71], v[144:147], v[208:211], v[68:71]
	v_mfma_f32_16x16x32_bf16 v[68:71], v[148:151], v[214:217], v[68:71]
	v_mfma_f32_16x16x32_bf16 v[64:67], v[168:171], v[208:211], v[64:67]
	v_mfma_f32_16x16x32_bf16 v[64:67], v[172:175], v[214:217], v[64:67]
	s_barrier
	s_add_i32 s33, s66, s19
	v_lshl_add_u64 v[218:219], s[52:53], 0, v[154:155]
	s_mov_b32 m0, s33
	ds_read_b128 v[176:179], v193 offset:16384
	ds_read_b128 v[180:183], v193 offset:17408
	ds_read_b128 v[184:187], v193 offset:18432
	ds_read_b128 v[196:199], v193 offset:19456
	ds_read_b128 v[200:203], v193 offset:20480
	ds_read_b128 v[204:207], v193 offset:21504
	ds_read_b128 v[208:211], v193 offset:22528
	ds_read_b128 v[214:217], v193 offset:23552
	global_load_lds_dwordx4 v[218:219], off
	s_add_i32 m0, s33, 0x2000
	s_add_u32 s74, s52, 0x160000
	v_lshl_add_u64 v[220:221], s[52:53], 0, v[158:159]
	s_addc_u32 s75, s53, 0
	s_add_i32 s33, s67, s19
	global_load_lds_dwordx4 v[220:221], off
	v_lshl_add_u64 v[222:223], s[74:75], 0, v[154:155]
	s_mov_b32 m0, s33
	v_lshl_add_u64 v[224:225], s[54:55], 0, v[156:157]
	global_load_lds_dwordx4 v[222:223], off
	s_add_i32 m0, s33, 0x2000
	v_lshl_add_u64 v[222:223], s[74:75], 0, v[158:159]
	global_load_lds_dwordx4 v[222:223], off
	s_mov_b32 m0, s56
	v_lshl_add_u64 v[222:223], s[54:55], 0, v[152:153]
	global_load_lds_dwordx4 v[222:223], off
	s_mov_b32 m0, s57
	s_nop 0
	global_load_lds_dwordx4 v[224:225], off
	s_waitcnt vmcnt(8) lgkmcnt(0)
	s_barrier
; #define PG8_STAGE(bufoff, gbase, voff) do { _Pragma("unroll") for (int _i = 0; _i < 2; ++_i) \
;         __builtin_amdgcn_global_load_lds((const unsigned*)((const char*)(gbase) + (voff)[_i]), (PG8_LAS unsigned*)(lds + (bufoff) + ldsw + _i * 8192), 16, 0, 0); } while (0)
; #define PG8_WAIT_V(n) asm volatile("s_waitcnt vmcnt(" #n ")" ::: "memory")
; #define PG8_WAIT_L(n) asm volatile("s_waitcnt lgkmcnt(" #n ")" ::: "memory")
; #define PG8_BAR __builtin_amdgcn_s_barrier()
; #define PG8_SCHED __builtin_amdgcn_sched_barrier(0)
;     ...
;             PG8_WAIT_V(8); PG8_WAIT_L(0); PG8_BAR; PG8_MMA(1, 0, At, B0); PG8_MMA(1, 1, At, B1); PG8_BAR; PG8_SCHED;
;             PG8_LDB(B0, 1, 0); PG8_LDB(B1, 1, 1); PG8_SCHED; PG8_LDA(At, 1, 0); PG8_STAGE(PG8_SA(0, 1), a2 + hstep, voffA);
;             PG8_WAIT_V(8); PG8_WAIT_L(0); PG8_BAR; PG8_MMA(0, 0, At, B0); PG8_MMA(0, 1, At, B1); PG8_BAR; PG8_SCHED;
	v_mfma_f32_16x16x32_bf16 v[60:63], v[128:131], v[176:179], v[60:63]
	v_mfma_f32_16x16x32_bf16 v[60:63], v[132:135], v[180:183], v[60:63]
	v_mfma_f32_16x16x32_bf16 v[56:59], v[136:139], v[176:179], v[56:59]
	v_mfma_f32_16x16x32_bf16 v[56:59], v[140:143], v[180:183], v[56:59]
	v_mfma_f32_16x16x32_bf16 v[44:47], v[128:131], v[184:187], v[44:47]
	v_mfma_f32_16x16x32_bf16 v[44:47], v[132:135], v[196:199], v[44:47]
	v_mfma_f32_16x16x32_bf16 v[40:43], v[136:139], v[184:187], v[40:43]
	v_mfma_f32_16x16x32_bf16 v[40:43], v[140:143], v[196:199], v[40:43]
	v_mfma_f32_16x16x32_bf16 v[28:31], v[128:131], v[200:203], v[28:31]
	v_mfma_f32_16x16x32_bf16 v[28:31], v[132:135], v[204:207], v[28:31]
	v_mfma_f32_16x16x32_bf16 v[24:27], v[136:139], v[200:203], v[24:27]
	v_mfma_f32_16x16x32_bf16 v[24:27], v[140:143], v[204:207], v[24:27]
	v_mfma_f32_16x16x32_bf16 v[12:15], v[128:131], v[208:211], v[12:15]
	v_mfma_f32_16x16x32_bf16 v[12:15], v[132:135], v[214:217], v[12:15]
	v_mfma_f32_16x16x32_bf16 v[8:11], v[136:139], v[208:211], v[8:11]
	v_mfma_f32_16x16x32_bf16 v[8:11], v[140:143], v[214:217], v[8:11]
	v_mfma_f32_16x16x32_bf16 v[52:55], v[144:147], v[176:179], v[52:55]
	v_mfma_f32_16x16x32_bf16 v[52:55], v[148:151], v[180:183], v[52:55]
	v_mfma_f32_16x16x32_bf16 v[48:51], v[168:171], v[176:179], v[48:51]
	v_mfma_f32_16x16x32_bf16 v[48:51], v[172:175], v[180:183], v[48:51]
	v_mfma_f32_16x16x32_bf16 v[36:39], v[144:147], v[184:187], v[36:39]
	v_mfma_f32_16x16x32_bf16 v[36:39], v[148:151], v[196:199], v[36:39]
	v_mfma_f32_16x16x32_bf16 v[32:35], v[168:171], v[184:187], v[32:35]
	v_mfma_f32_16x16x32_bf16 v[32:35], v[172:175], v[196:199], v[32:35]
	v_mfma_f32_16x16x32_bf16 v[20:23], v[144:147], v[200:203], v[20:23]
	v_mfma_f32_16x16x32_bf16 v[20:23], v[148:151], v[204:207], v[20:23]
	v_mfma_f32_16x16x32_bf16 v[16:19], v[168:171], v[200:203], v[16:19]
	v_mfma_f32_16x16x32_bf16 v[16:19], v[172:175], v[204:207], v[16:19]
	v_mfma_f32_16x16x32_bf16 v[4:7], v[144:147], v[208:211], v[4:7]
	v_mfma_f32_16x16x32_bf16 v[4:7], v[148:151], v[214:217], v[4:7]
	v_mfma_f32_16x16x32_bf16 v[0:3], v[168:171], v[208:211], v[0:3]
	v_mfma_f32_16x16x32_bf16 v[0:3], v[172:175], v[214:217], v[0:3]
	s_barrier
	s_add_i32 s33, 0, 0x18000
	s_add_i32 s73, 0, 0x1c000
	v_add_u32_e32 v140, s33, v189
	v_add_u32_e32 v172, s73, v189
	ds_read_b128 v[128:131], v140
	ds_read_b128 v[132:135], v140 offset:1024
	ds_read_b128 v[136:139], v140 offset:2048
	ds_read_b128 v[140:143], v140 offset:3072
	ds_read_b128 v[144:147], v172
	ds_read_b128 v[148:151], v172 offset:1024
	ds_read_b128 v[168:171], v172 offset:2048
	ds_read_b128 v[172:175], v172 offset:3072
	s_add_u32 s54, s54, 0x160000
	s_addc_u32 s55, s55, 0
	s_mov_b32 m0, s58
	v_lshl_add_u64 v[226:227], s[54:55], 0, v[152:153]
	ds_read_b128 v[176:179], v193 offset:32768
	ds_read_b128 v[180:183], v193 offset:33792
	ds_read_b128 v[184:187], v193 offset:34816
	ds_read_b128 v[196:199], v193 offset:35840
	ds_read_b128 v[200:203], v193 offset:36864
	ds_read_b128 v[204:207], v193 offset:37888
	ds_read_b128 v[208:211], v193 offset:38912
	ds_read_b128 v[214:217], v193 offset:39936
	global_load_lds_dwordx4 v[226:227], off
	s_mov_b32 m0, s59
	v_lshl_add_u64 v[226:227], s[54:55], 0, v[156:157]
	global_load_lds_dwordx4 v[226:227], off
	s_waitcnt vmcnt(8) lgkmcnt(0)
	s_barrier
	v_mfma_f32_16x16x32_bf16 v[124:127], v[128:131], v[176:179], v[124:127]
	v_mfma_f32_16x16x32_bf16 v[124:127], v[132:135], v[180:183], v[124:127]
	v_mfma_f32_16x16x32_bf16 v[120:123], v[136:139], v[176:179], v[120:123]
	v_mfma_f32_16x16x32_bf16 v[120:123], v[140:143], v[180:183], v[120:123]
	v_mfma_f32_16x16x32_bf16 v[108:111], v[128:131], v[184:187], v[108:111]
	v_mfma_f32_16x16x32_bf16 v[108:111], v[132:135], v[196:199], v[108:111]
	v_mfma_f32_16x16x32_bf16 v[104:107], v[136:139], v[184:187], v[104:107]
	v_mfma_f32_16x16x32_bf16 v[104:107], v[140:143], v[196:199], v[104:107]
	v_mfma_f32_16x16x32_bf16 v[92:95], v[128:131], v[200:203], v[92:95]
	v_mfma_f32_16x16x32_bf16 v[92:95], v[132:135], v[204:207], v[92:95]
	v_mfma_f32_16x16x32_bf16 v[88:91], v[136:139], v[200:203], v[88:91]
	v_mfma_f32_16x16x32_bf16 v[88:91], v[140:143], v[204:207], v[88:91]
	v_mfma_f32_16x16x32_bf16 v[76:79], v[128:131], v[208:211], v[76:79]
	v_mfma_f32_16x16x32_bf16 v[76:79], v[132:135], v[214:217], v[76:79]
	v_mfma_f32_16x16x32_bf16 v[72:75], v[136:139], v[208:211], v[72:75]
	v_mfma_f32_16x16x32_bf16 v[72:75], v[140:143], v[214:217], v[72:75]
	v_mfma_f32_16x16x32_bf16 v[116:119], v[144:147], v[176:179], v[116:119]
	v_mfma_f32_16x16x32_bf16 v[116:119], v[148:151], v[180:183], v[116:119]
	v_mfma_f32_16x16x32_bf16 v[112:115], v[168:171], v[176:179], v[112:115]
	v_mfma_f32_16x16x32_bf16 v[112:115], v[172:175], v[180:183], v[112:115]
	v_mfma_f32_16x16x32_bf16 v[100:103], v[144:147], v[184:187], v[100:103]
	v_mfma_f32_16x16x32_bf16 v[100:103], v[148:151], v[196:199], v[100:103]
	v_mfma_f32_16x16x32_bf16 v[96:99], v[168:171], v[184:187], v[96:99]
	v_mfma_f32_16x16x32_bf16 v[96:99], v[172:175], v[196:199], v[96:99]
	v_mfma_f32_16x16x32_bf16 v[84:87], v[144:147], v[200:203], v[84:87]
	v_mfma_f32_16x16x32_bf16 v[84:87], v[148:151], v[204:207], v[84:87]
	v_mfma_f32_16x16x32_bf16 v[80:83], v[168:171], v[200:203], v[80:83]
	v_mfma_f32_16x16x32_bf16 v[80:83], v[172:175], v[204:207], v[80:83]
	v_mfma_f32_16x16x32_bf16 v[68:71], v[144:147], v[208:211], v[68:71]
	v_mfma_f32_16x16x32_bf16 v[68:71], v[148:151], v[214:217], v[68:71]
	v_mfma_f32_16x16x32_bf16 v[64:67], v[168:171], v[208:211], v[64:67]
	v_mfma_f32_16x16x32_bf16 v[64:67], v[172:175], v[214:217], v[64:67]
	s_barrier
; #define PG8_STAGE(bufoff, gbase, voff) do { _Pragma("unroll") for (int _i = 0; _i < 2; ++_i) \
;         __builtin_amdgcn_global_load_lds((const unsigned*)((const char*)(gbase) + (voff)[_i]), (PG8_LAS unsigned*)(lds + (bufoff) + ldsw + _i * 8192), 16, 0, 0); } while (0)
; #define PG8_WAIT_V(n) asm volatile("s_waitcnt vmcnt(" #n ")" ::: "memory")
; #define PG8_WAIT_L(n) asm volatile("s_waitcnt lgkmcnt(" #n ")" ::: "memory")
; #define PG8_BAR __builtin_amdgcn_s_barrier()
; #define PG8_SCHED __builtin_amdgcn_sched_barrier(0)
;     ...
;             PG8_LDA(At, 1, 1); PG8_STAGE(PG8_SB(1, 0), b3, voffB); PG8_STAGE(PG8_SB(1, 1), b3 + hstep, voffB); PG8_STAGE(PG8_SA(1, 0), a3, voffA);
;             PG8_WAIT_V(8); PG8_WAIT_L(0); PG8_BAR; PG8_MMA(1, 0, At, B0); PG8_MMA(1, 1, At, B1); PG8_BAR; PG8_SCHED;
;     ...
;         if constexpr (ALIGN_EPI) { if (wr == 0) PG8_BAR; }
	s_add_i32 s33, s33, s19
	v_lshl_add_u64 v[218:219], v[218:219], 0, s[24:25]
	s_mov_b32 m0, s33
	ds_read_b128 v[176:179], v193 offset:49152
	ds_read_b128 v[180:183], v193 offset:50176
	ds_read_b128 v[184:187], v193 offset:51200
	ds_read_b128 v[196:199], v193 offset:52224
	ds_read_b128 v[200:203], v193 offset:53248
	ds_read_b128 v[204:207], v193 offset:54272
	ds_read_b128 v[208:211], v193 offset:55296
	ds_read_b128 v[214:217], v193 offset:56320
	global_load_lds_dwordx4 v[218:219], off
	s_add_i32 m0, s33, 0x2000
	s_add_u32 s52, s52, 0x160080
	v_lshl_add_u64 v[218:219], v[220:221], 0, s[24:25]
	s_addc_u32 s53, s53, 0
	s_add_i32 s33, s73, s19
	global_load_lds_dwordx4 v[218:219], off
	s_mov_b32 m0, s33
	v_lshl_add_u64 v[218:219], s[52:53], 0, v[154:155]
	global_load_lds_dwordx4 v[218:219], off
	s_add_i32 m0, s33, 0x2000
	v_lshl_add_u64 v[218:219], s[52:53], 0, v[158:159]
	global_load_lds_dwordx4 v[218:219], off
	s_mov_b32 m0, s61
	v_lshl_add_u64 v[218:219], v[222:223], 0, s[24:25]
	global_load_lds_dwordx4 v[218:219], off
	s_mov_b32 m0, s62
	v_lshl_add_u64 v[218:219], v[224:225], 0, s[24:25]
	global_load_lds_dwordx4 v[218:219], off
	s_waitcnt vmcnt(8) lgkmcnt(0)
	s_barrier
	v_mfma_f32_16x16x32_bf16 v[60:63], v[128:131], v[176:179], v[60:63]
	v_mfma_f32_16x16x32_bf16 v[60:63], v[132:135], v[180:183], v[60:63]
	v_mfma_f32_16x16x32_bf16 v[56:59], v[136:139], v[176:179], v[56:59]
	v_mfma_f32_16x16x32_bf16 v[56:59], v[140:143], v[180:183], v[56:59]
	v_mfma_f32_16x16x32_bf16 v[44:47], v[128:131], v[184:187], v[44:47]
	v_mfma_f32_16x16x32_bf16 v[44:47], v[132:135], v[196:199], v[44:47]
	v_mfma_f32_16x16x32_bf16 v[40:43], v[136:139], v[184:187], v[40:43]
	v_mfma_f32_16x16x32_bf16 v[40:43], v[140:143], v[196:199], v[40:43]
	v_mfma_f32_16x16x32_bf16 v[28:31], v[128:131], v[200:203], v[28:31]
	v_mfma_f32_16x16x32_bf16 v[28:31], v[132:135], v[204:207], v[28:31]
	v_mfma_f32_16x16x32_bf16 v[24:27], v[136:139], v[200:203], v[24:27]
	v_mfma_f32_16x16x32_bf16 v[24:27], v[140:143], v[204:207], v[24:27]
	v_mfma_f32_16x16x32_bf16 v[12:15], v[128:131], v[208:211], v[12:15]
	v_mfma_f32_16x16x32_bf16 v[12:15], v[132:135], v[214:217], v[12:15]
	v_mfma_f32_16x16x32_bf16 v[8:11], v[136:139], v[208:211], v[8:11]
	v_mfma_f32_16x16x32_bf16 v[8:11], v[140:143], v[214:217], v[8:11]
	v_mfma_f32_16x16x32_bf16 v[52:55], v[144:147], v[176:179], v[52:55]
	v_mfma_f32_16x16x32_bf16 v[52:55], v[148:151], v[180:183], v[52:55]
	v_mfma_f32_16x16x32_bf16 v[48:51], v[168:171], v[176:179], v[48:51]
	v_mfma_f32_16x16x32_bf16 v[48:51], v[172:175], v[180:183], v[48:51]
	v_mfma_f32_16x16x32_bf16 v[36:39], v[144:147], v[184:187], v[36:39]
	v_mfma_f32_16x16x32_bf16 v[36:39], v[148:151], v[196:199], v[36:39]
	v_mfma_f32_16x16x32_bf16 v[32:35], v[168:171], v[184:187], v[32:35]
	v_mfma_f32_16x16x32_bf16 v[32:35], v[172:175], v[196:199], v[32:35]
	v_mfma_f32_16x16x32_bf16 v[20:23], v[144:147], v[200:203], v[20:23]
	v_mfma_f32_16x16x32_bf16 v[20:23], v[148:151], v[204:207], v[20:23]
	v_mfma_f32_16x16x32_bf16 v[16:19], v[168:171], v[200:203], v[16:19]
	v_mfma_f32_16x16x32_bf16 v[16:19], v[172:175], v[204:207], v[16:19]
	v_mfma_f32_16x16x32_bf16 v[4:7], v[144:147], v[208:211], v[4:7]
	v_mfma_f32_16x16x32_bf16 v[4:7], v[148:151], v[214:217], v[4:7]
	v_mfma_f32_16x16x32_bf16 v[0:3], v[168:171], v[208:211], v[0:3]
	v_mfma_f32_16x16x32_bf16 v[0:3], v[172:175], v[214:217], v[0:3]
	s_barrier
	s_add_i32 s72, s72, 2
	s_add_u32 s50, s50, 0x100
	s_addc_u32 s51, s51, 0
	s_add_u32 s34, s34, 0x100
	s_addc_u32 s35, s35, 0
	s_cmpk_gt_u32 s72, 0x55
	s_cbranch_scc0 .LBB0_335
	s_and_b64 vcc, exec, s[44:45]
	s_cbranch_vccz .LBB0_338
	s_barrier

; #define PG8_STAGE(bufoff, gbase, voff) do { _Pragma("unroll") for (int _i = 0; _i < 2; ++_i) \
;         __builtin_amdgcn_global_load_lds((const unsigned*)((const char*)(gbase) + (voff)[_i]), (PG8_LAS unsigned*)(lds + (bufoff) + ldsw + _i * 8192), 16, 0, 0); } while (0)
; #define PG8_WAIT_V(n) asm volatile("s_waitcnt vmcnt(" #n ")" ::: "memory")
; #define PG8_WAIT_L(n) asm volatile("s_waitcnt lgkmcnt(" #n ")" ::: "memory")
; #define PG8_BAR __builtin_amdgcn_s_barrier()
; #define PG8_SCHED __builtin_amdgcn_sched_barrier(0)
;     ...
;             const bool last = (t == nt - 2);
;             const char* a1 = cA + (size_t)(t + 1) * kstep;
;             const char* a2 = last ? nA : cA + (size_t)(t + 2) * kstep; const char* b2 = last ? nB : cB + (size_t)(t + 2) * kstep;
;             const char* a3 = a2 + kstep; const char* b3 = b2 + kstep;
;             if (last && has_next) S.a_ready(nxt);
;             if (last) E.pre(pre, cur, wr, fr);
;             if constexpr (MIDK > 0) { if (t == MIDK / BK) E.mid(acc, cur, wr, wc, fr, fq); }
;             if constexpr (SP2) {
;             PG8_LDB(B0, 0, 0); PG8_LDB(B1, 0, 1); PG8_SCHED; PG8_LDA(At, 0, 0); PG8_STAGE(PG8_SA(1, 1), a1 + hstep, voffA);
;             PG8_WAIT_V(8); PG8_WAIT_L(0); PG8_BAR; PG8_MMA(0, 0, At, B0); PG8_MMA(0, 1, At, B1); PG8_BAR; PG8_SCHED;
;             PG8_LDA(At, 0, 1); PG8_STAGE(PG8_SB(0, 0), b2, voffB); PG8_STAGE(PG8_SB(0, 1), b2 + hstep, voffB); PG8_STAGE(PG8_SA(0, 0), a2, voffA);
;             PG8_WAIT_V(8); PG8_WAIT_L(0); PG8_BAR; PG8_MMA(1, 0, At, B0); PG8_MMA(1, 1, At, B1); PG8_BAR; PG8_SCHED;
.LBB0_432:
	v_add_u32_e32 v142, s91, v205
	v_add_u32_e32 v146, s92, v205
	ds_read_b128 v[130:133], v142
	ds_read_b128 v[134:137], v142 offset:1024
	s_waitcnt lgkmcnt(0)
	ds_read_b128 v[138:141], v142 offset:2048
	ds_read_b128 v[142:145], v142 offset:3072
	ds_read_b128 v[188:191], v146
	ds_read_b128 v[192:195], v146 offset:1024
	ds_read_b128 v[196:199], v146 offset:2048
	ds_read_b128 v[200:203], v146 offset:3072
	s_add_u32 s33, s70, 0xfff80080
	s_addc_u32 s74, s71, -1
	s_and_b64 s[72:73], s[72:73], exec
	s_cselect_b32 s75, s18, s74
	s_cselect_b32 s74, s19, s33
	s_cselect_b32 s73, s34, s61
	s_cselect_b32 s72, s35, s10
	v_lshl_add_u64 v[146:147], s[70:71], 0, v[162:163]
	s_add_i32 m0, s69, 0xc000
	ds_read_b128 v[214:217], v159
	ds_read_b128 v[218:221], v159 offset:1024
	ds_read_b128 v[222:225], v159 offset:2048
	ds_read_b128 v[226:229], v159 offset:3072
	ds_read_b128 v[230:233], v159 offset:4096
	ds_read_b128 v[234:237], v159 offset:5120
	ds_read_b128 v[238:241], v159 offset:6144
	ds_read_b128 v[242:245], v159 offset:7168
	global_load_lds_dwordx4 v[146:147], off
	s_add_i32 m0, s69, 0xe000
	v_lshl_add_u64 v[146:147], s[70:71], 0, v[164:165]
	global_load_lds_dwordx4 v[146:147], off
	s_waitcnt vmcnt(8) lgkmcnt(0)
	s_barrier
	v_mfma_f32_16x16x32_bf16 v[124:127], v[130:133], v[214:217], v[124:127]
	v_mfma_f32_16x16x32_bf16 v[124:127], v[134:137], v[218:221], v[124:127]
	v_mfma_f32_16x16x32_bf16 v[120:123], v[138:141], v[214:217], v[120:123]
	v_mfma_f32_16x16x32_bf16 v[120:123], v[142:145], v[218:221], v[120:123]
	v_mfma_f32_16x16x32_bf16 v[108:111], v[130:133], v[222:225], v[108:111]
	v_mfma_f32_16x16x32_bf16 v[108:111], v[134:137], v[226:229], v[108:111]
	v_mfma_f32_16x16x32_bf16 v[104:107], v[138:141], v[222:225], v[104:107]
	v_mfma_f32_16x16x32_bf16 v[104:107], v[142:145], v[226:229], v[104:107]
	v_mfma_f32_16x16x32_bf16 v[92:95], v[130:133], v[230:233], v[92:95]
	v_mfma_f32_16x16x32_bf16 v[92:95], v[134:137], v[234:237], v[92:95]
	v_mfma_f32_16x16x32_bf16 v[88:91], v[138:141], v[230:233], v[88:91]
	v_mfma_f32_16x16x32_bf16 v[88:91], v[142:145], v[234:237], v[88:91]
	v_mfma_f32_16x16x32_bf16 v[76:79], v[130:133], v[238:241], v[76:79]
	v_mfma_f32_16x16x32_bf16 v[76:79], v[134:137], v[242:245], v[76:79]
	v_mfma_f32_16x16x32_bf16 v[72:75], v[138:141], v[238:241], v[72:75]
	v_mfma_f32_16x16x32_bf16 v[72:75], v[142:145], v[242:245], v[72:75]
	v_mfma_f32_16x16x32_bf16 v[116:119], v[188:191], v[214:217], v[116:119]
	v_mfma_f32_16x16x32_bf16 v[116:119], v[192:195], v[218:221], v[116:119]
	v_mfma_f32_16x16x32_bf16 v[112:115], v[196:199], v[214:217], v[112:115]
	v_mfma_f32_16x16x32_bf16 v[112:115], v[200:203], v[218:221], v[112:115]
	v_mfma_f32_16x16x32_bf16 v[100:103], v[188:191], v[222:225], v[100:103]
	v_mfma_f32_16x16x32_bf16 v[100:103], v[192:195], v[226:229], v[100:103]
	v_mfma_f32_16x16x32_bf16 v[96:99], v[196:199], v[222:225], v[96:99]
	v_mfma_f32_16x16x32_bf16 v[96:99], v[200:203], v[226:229], v[96:99]
	v_mfma_f32_16x16x32_bf16 v[84:87], v[188:191], v[230:233], v[84:87]
	v_mfma_f32_16x16x32_bf16 v[84:87], v[192:195], v[234:237], v[84:87]
	v_mfma_f32_16x16x32_bf16 v[80:83], v[196:199], v[230:233], v[80:83]
	v_mfma_f32_16x16x32_bf16 v[80:83], v[200:203], v[234:237], v[80:83]
	v_mfma_f32_16x16x32_bf16 v[68:71], v[188:191], v[238:241], v[68:71]
	v_mfma_f32_16x16x32_bf16 v[68:71], v[192:195], v[242:245], v[68:71]
	v_mfma_f32_16x16x32_bf16 v[64:67], v[196:199], v[238:241], v[64:67]
	v_mfma_f32_16x16x32_bf16 v[64:67], v[200:203], v[242:245], v[64:67]
	s_barrier
	s_add_i32 s33, s91, s82
	v_lshl_add_u64 v[146:147], s[72:73], 0, v[150:151]
	s_mov_b32 m0, s33
	ds_read_b128 v[214:217], v159 offset:16384
	ds_read_b128 v[218:221], v159 offset:17408
	ds_read_b128 v[222:225], v159 offset:18432
	ds_read_b128 v[226:229], v159 offset:19456
	ds_read_b128 v[230:233], v159 offset:20480
	ds_read_b128 v[234:237], v159 offset:21504
	ds_read_b128 v[238:241], v159 offset:22528
	ds_read_b128 v[242:245], v159 offset:23552
	global_load_lds_dwordx4 v[146:147], off
	s_add_i32 m0, s33, 0x2000
	s_add_u32 s94, s72, 0x80000
	v_lshl_add_u64 v[246:247], s[72:73], 0, v[154:155]
	s_addc_u32 s95, s73, 0
	s_add_i32 s33, s92, s82
	global_load_lds_dwordx4 v[246:247], off
	v_lshl_add_u64 v[248:249], s[94:95], 0, v[150:151]
	s_mov_b32 m0, s33
	v_lshl_add_u64 v[250:251], s[74:75], 0, v[152:153]
	global_load_lds_dwordx4 v[248:249], off
	s_add_i32 m0, s33, 0x2000
	v_lshl_add_u64 v[248:249], s[94:95], 0, v[154:155]
	global_load_lds_dwordx4 v[248:249], off
	s_mov_b32 m0, s69
	v_lshl_add_u64 v[248:249], s[74:75], 0, v[148:149]
	global_load_lds_dwordx4 v[248:249], off
	s_mov_b32 m0, s83
	s_nop 0
	global_load_lds_dwordx4 v[250:251], off
	s_waitcnt vmcnt(8) lgkmcnt(0)
	s_barrier
; #define PG8_STAGE(bufoff, gbase, voff) do { _Pragma("unroll") for (int _i = 0; _i < 2; ++_i) \
;         __builtin_amdgcn_global_load_lds((const unsigned*)((const char*)(gbase) + (voff)[_i]), (PG8_LAS unsigned*)(lds + (bufoff) + ldsw + _i * 8192), 16, 0, 0); } while (0)
; #define PG8_WAIT_V(n) asm volatile("s_waitcnt vmcnt(" #n ")" ::: "memory")
; #define PG8_WAIT_L(n) asm volatile("s_waitcnt lgkmcnt(" #n ")" ::: "memory")
; #define PG8_BAR __builtin_amdgcn_s_barrier()
; #define PG8_SCHED __builtin_amdgcn_sched_barrier(0)
;     ...
;             PG8_WAIT_V(8); PG8_WAIT_L(0); PG8_BAR; PG8_MMA(1, 0, At, B0); PG8_MMA(1, 1, At, B1); PG8_BAR; PG8_SCHED;
;             PG8_LDB(B0, 1, 0); PG8_LDB(B1, 1, 1); PG8_SCHED; PG8_LDA(At, 1, 0); PG8_STAGE(PG8_SA(0, 1), a2 + hstep, voffA);
;             PG8_WAIT_V(8); PG8_WAIT_L(0); PG8_BAR; PG8_MMA(0, 0, At, B0); PG8_MMA(0, 1, At, B1); PG8_BAR; PG8_SCHED;
	v_mfma_f32_16x16x32_bf16 v[60:63], v[130:133], v[214:217], v[60:63]
	v_mfma_f32_16x16x32_bf16 v[60:63], v[134:137], v[218:221], v[60:63]
	v_mfma_f32_16x16x32_bf16 v[56:59], v[138:141], v[214:217], v[56:59]
	v_mfma_f32_16x16x32_bf16 v[56:59], v[142:145], v[218:221], v[56:59]
	v_mfma_f32_16x16x32_bf16 v[44:47], v[130:133], v[222:225], v[44:47]
	v_mfma_f32_16x16x32_bf16 v[44:47], v[134:137], v[226:229], v[44:47]
	v_mfma_f32_16x16x32_bf16 v[40:43], v[138:141], v[222:225], v[40:43]
	v_mfma_f32_16x16x32_bf16 v[40:43], v[142:145], v[226:229], v[40:43]
	v_mfma_f32_16x16x32_bf16 v[28:31], v[130:133], v[230:233], v[28:31]
	v_mfma_f32_16x16x32_bf16 v[28:31], v[134:137], v[234:237], v[28:31]
	v_mfma_f32_16x16x32_bf16 v[24:27], v[138:141], v[230:233], v[24:27]
	v_mfma_f32_16x16x32_bf16 v[24:27], v[142:145], v[234:237], v[24:27]
	v_mfma_f32_16x16x32_bf16 v[12:15], v[130:133], v[238:241], v[12:15]
	v_mfma_f32_16x16x32_bf16 v[12:15], v[134:137], v[242:245], v[12:15]
	v_mfma_f32_16x16x32_bf16 v[8:11], v[138:141], v[238:241], v[8:11]
	v_mfma_f32_16x16x32_bf16 v[8:11], v[142:145], v[242:245], v[8:11]
	v_mfma_f32_16x16x32_bf16 v[52:55], v[188:191], v[214:217], v[52:55]
	v_mfma_f32_16x16x32_bf16 v[52:55], v[192:195], v[218:221], v[52:55]
	v_mfma_f32_16x16x32_bf16 v[48:51], v[196:199], v[214:217], v[48:51]
	v_mfma_f32_16x16x32_bf16 v[48:51], v[200:203], v[218:221], v[48:51]
	v_mfma_f32_16x16x32_bf16 v[36:39], v[188:191], v[222:225], v[36:39]
	v_mfma_f32_16x16x32_bf16 v[36:39], v[192:195], v[226:229], v[36:39]
	v_mfma_f32_16x16x32_bf16 v[32:35], v[196:199], v[222:225], v[32:35]
	v_mfma_f32_16x16x32_bf16 v[32:35], v[200:203], v[226:229], v[32:35]
	v_mfma_f32_16x16x32_bf16 v[20:23], v[188:191], v[230:233], v[20:23]
	v_mfma_f32_16x16x32_bf16 v[20:23], v[192:195], v[234:237], v[20:23]
	v_mfma_f32_16x16x32_bf16 v[16:19], v[196:199], v[230:233], v[16:19]
	v_mfma_f32_16x16x32_bf16 v[16:19], v[200:203], v[234:237], v[16:19]
	v_mfma_f32_16x16x32_bf16 v[4:7], v[188:191], v[238:241], v[4:7]
	v_mfma_f32_16x16x32_bf16 v[4:7], v[192:195], v[242:245], v[4:7]
	v_mfma_f32_16x16x32_bf16 v[0:3], v[196:199], v[238:241], v[0:3]
	v_mfma_f32_16x16x32_bf16 v[0:3], v[200:203], v[242:245], v[0:3]
	s_barrier
	s_add_i32 s33, 0, 0x18000
	s_add_i32 s94, 0, 0x1c000
	v_add_u32_e32 v142, s33, v205
	v_add_u32_e32 v156, s94, v205
	ds_read_b128 v[130:133], v142
	ds_read_b128 v[134:137], v142 offset:1024
	ds_read_b128 v[138:141], v142 offset:2048
	ds_read_b128 v[142:145], v142 offset:3072
	ds_read_b128 v[188:191], v156
	ds_read_b128 v[192:195], v156 offset:1024
	ds_read_b128 v[196:199], v156 offset:2048
	ds_read_b128 v[200:203], v156 offset:3072
	s_add_u32 s74, s74, 0x80000
	s_addc_u32 s75, s75, 0
	s_mov_b32 m0, s84
	v_lshl_add_u64 v[252:253], s[74:75], 0, v[148:149]
	ds_read_b128 v[214:217], v159 offset:32768
	ds_read_b128 v[218:221], v159 offset:33792
	ds_read_b128 v[222:225], v159 offset:34816
	ds_read_b128 v[226:229], v159 offset:35840
	ds_read_b128 v[230:233], v159 offset:36864
	ds_read_b128 v[234:237], v159 offset:37888
	ds_read_b128 v[238:241], v159 offset:38912
	ds_read_b128 v[242:245], v159 offset:39936
	global_load_lds_dwordx4 v[252:253], off
	s_mov_b32 m0, s85
	v_lshl_add_u64 v[252:253], s[74:75], 0, v[152:153]
	global_load_lds_dwordx4 v[252:253], off
	s_waitcnt vmcnt(8) lgkmcnt(0)
	s_barrier
	v_mfma_f32_16x16x32_bf16 v[124:127], v[130:133], v[214:217], v[124:127]
	v_mfma_f32_16x16x32_bf16 v[124:127], v[134:137], v[218:221], v[124:127]
	v_mfma_f32_16x16x32_bf16 v[120:123], v[138:141], v[214:217], v[120:123]
	v_mfma_f32_16x16x32_bf16 v[120:123], v[142:145], v[218:221], v[120:123]
	v_mfma_f32_16x16x32_bf16 v[108:111], v[130:133], v[222:225], v[108:111]
	v_mfma_f32_16x16x32_bf16 v[108:111], v[134:137], v[226:229], v[108:111]
	v_mfma_f32_16x16x32_bf16 v[104:107], v[138:141], v[222:225], v[104:107]
	v_mfma_f32_16x16x32_bf16 v[104:107], v[142:145], v[226:229], v[104:107]
	v_mfma_f32_16x16x32_bf16 v[92:95], v[130:133], v[230:233], v[92:95]
	v_mfma_f32_16x16x32_bf16 v[92:95], v[134:137], v[234:237], v[92:95]
	v_mfma_f32_16x16x32_bf16 v[88:91], v[138:141], v[230:233], v[88:91]
	v_mfma_f32_16x16x32_bf16 v[88:91], v[142:145], v[234:237], v[88:91]
	v_mfma_f32_16x16x32_bf16 v[76:79], v[130:133], v[238:241], v[76:79]
	v_mfma_f32_16x16x32_bf16 v[76:79], v[134:137], v[242:245], v[76:79]
	v_mfma_f32_16x16x32_bf16 v[72:75], v[138:141], v[238:241], v[72:75]
	v_mfma_f32_16x16x32_bf16 v[72:75], v[142:145], v[242:245], v[72:75]
	v_mfma_f32_16x16x32_bf16 v[116:119], v[188:191], v[214:217], v[116:119]
	v_mfma_f32_16x16x32_bf16 v[116:119], v[192:195], v[218:221], v[116:119]
	v_mfma_f32_16x16x32_bf16 v[112:115], v[196:199], v[214:217], v[112:115]
	v_mfma_f32_16x16x32_bf16 v[112:115], v[200:203], v[218:221], v[112:115]
	v_mfma_f32_16x16x32_bf16 v[100:103], v[188:191], v[222:225], v[100:103]
	v_mfma_f32_16x16x32_bf16 v[100:103], v[192:195], v[226:229], v[100:103]
	v_mfma_f32_16x16x32_bf16 v[96:99], v[196:199], v[222:225], v[96:99]
	v_mfma_f32_16x16x32_bf16 v[96:99], v[200:203], v[226:229], v[96:99]
	v_mfma_f32_16x16x32_bf16 v[84:87], v[188:191], v[230:233], v[84:87]
	v_mfma_f32_16x16x32_bf16 v[84:87], v[192:195], v[234:237], v[84:87]
	v_mfma_f32_16x16x32_bf16 v[80:83], v[196:199], v[230:233], v[80:83]
	v_mfma_f32_16x16x32_bf16 v[80:83], v[200:203], v[234:237], v[80:83]
	v_mfma_f32_16x16x32_bf16 v[68:71], v[188:191], v[238:241], v[68:71]
	v_mfma_f32_16x16x32_bf16 v[68:71], v[192:195], v[242:245], v[68:71]
	v_mfma_f32_16x16x32_bf16 v[64:67], v[196:199], v[238:241], v[64:67]
	v_mfma_f32_16x16x32_bf16 v[64:67], v[200:203], v[242:245], v[64:67]
	s_barrier
; #define PG8_STAGE(bufoff, gbase, voff) do { _Pragma("unroll") for (int _i = 0; _i < 2; ++_i) \
;         __builtin_amdgcn_global_load_lds((const unsigned*)((const char*)(gbase) + (voff)[_i]), (PG8_LAS unsigned*)(lds + (bufoff) + ldsw + _i * 8192), 16, 0, 0); } while (0)
; #define PG8_WAIT_V(n) asm volatile("s_waitcnt vmcnt(" #n ")" ::: "memory")
; #define PG8_WAIT_L(n) asm volatile("s_waitcnt lgkmcnt(" #n ")" ::: "memory")
; #define PG8_BAR __builtin_amdgcn_s_barrier()
; #define PG8_SCHED __builtin_amdgcn_sched_barrier(0)
;     ...
;             PG8_LDA(At, 1, 1); PG8_STAGE(PG8_SB(1, 0), b3, voffB); PG8_STAGE(PG8_SB(1, 1), b3 + hstep, voffB); PG8_STAGE(PG8_SA(1, 0), a3, voffA);
;             PG8_WAIT_V(8); PG8_WAIT_L(0); PG8_BAR; PG8_MMA(1, 0, At, B0); PG8_MMA(1, 1, At, B1); PG8_BAR; PG8_SCHED;
	s_add_i32 s33, s33, s82
	v_lshl_add_u64 v[146:147], v[146:147], 0, s[50:51]
	s_mov_b32 m0, s33
	ds_read_b128 v[214:217], v159 offset:49152
	ds_read_b128 v[218:221], v159 offset:50176
	ds_read_b128 v[222:225], v159 offset:51200
	ds_read_b128 v[226:229], v159 offset:52224
	ds_read_b128 v[230:233], v159 offset:53248
	ds_read_b128 v[234:237], v159 offset:54272
	ds_read_b128 v[238:241], v159 offset:55296
	ds_read_b128 v[242:245], v159 offset:56320
	global_load_lds_dwordx4 v[146:147], off
	s_add_i32 m0, s33, 0x2000
	s_add_u32 s72, s72, 0x80080
	v_lshl_add_u64 v[146:147], v[246:247], 0, s[50:51]
	s_addc_u32 s73, s73, 0
	s_add_i32 s33, s94, s82
	global_load_lds_dwordx4 v[146:147], off
	s_mov_b32 m0, s33
	v_lshl_add_u64 v[146:147], s[72:73], 0, v[150:151]
	global_load_lds_dwordx4 v[146:147], off
	s_add_i32 m0, s33, 0x2000
	v_lshl_add_u64 v[146:147], s[72:73], 0, v[154:155]
	global_load_lds_dwordx4 v[146:147], off
	s_mov_b32 m0, s86
	v_lshl_add_u64 v[146:147], v[248:249], 0, s[50:51]
	global_load_lds_dwordx4 v[146:147], off
	s_mov_b32 m0, s87
	v_lshl_add_u64 v[146:147], v[250:251], 0, s[50:51]
	global_load_lds_dwordx4 v[146:147], off
	s_waitcnt vmcnt(8) lgkmcnt(0)
	s_barrier
	v_mfma_f32_16x16x32_bf16 v[60:63], v[130:133], v[214:217], v[60:63]
	v_mfma_f32_16x16x32_bf16 v[60:63], v[134:137], v[218:221], v[60:63]
	v_mfma_f32_16x16x32_bf16 v[56:59], v[138:141], v[214:217], v[56:59]
	v_mfma_f32_16x16x32_bf16 v[56:59], v[142:145], v[218:221], v[56:59]
	v_mfma_f32_16x16x32_bf16 v[44:47], v[130:133], v[222:225], v[44:47]
	v_mfma_f32_16x16x32_bf16 v[44:47], v[134:137], v[226:229], v[44:47]
	v_mfma_f32_16x16x32_bf16 v[40:43], v[138:141], v[222:225], v[40:43]
	v_mfma_f32_16x16x32_bf16 v[40:43], v[142:145], v[226:229], v[40:43]
	v_mfma_f32_16x16x32_bf16 v[28:31], v[130:133], v[230:233], v[28:31]
	v_mfma_f32_16x16x32_bf16 v[28:31], v[134:137], v[234:237], v[28:31]
	v_mfma_f32_16x16x32_bf16 v[24:27], v[138:141], v[230:233], v[24:27]
	v_mfma_f32_16x16x32_bf16 v[24:27], v[142:145], v[234:237], v[24:27]
	v_mfma_f32_16x16x32_bf16 v[12:15], v[130:133], v[238:241], v[12:15]
	v_mfma_f32_16x16x32_bf16 v[12:15], v[134:137], v[242:245], v[12:15]
	v_mfma_f32_16x16x32_bf16 v[8:11], v[138:141], v[238:241], v[8:11]
	v_mfma_f32_16x16x32_bf16 v[8:11], v[142:145], v[242:245], v[8:11]
	v_mfma_f32_16x16x32_bf16 v[52:55], v[188:191], v[214:217], v[52:55]
	v_mfma_f32_16x16x32_bf16 v[52:55], v[192:195], v[218:221], v[52:55]
	v_mfma_f32_16x16x32_bf16 v[48:51], v[196:199], v[214:217], v[48:51]
	v_mfma_f32_16x16x32_bf16 v[48:51], v[200:203], v[218:221], v[48:51]
	v_mfma_f32_16x16x32_bf16 v[36:39], v[188:191], v[222:225], v[36:39]
	v_mfma_f32_16x16x32_bf16 v[36:39], v[192:195], v[226:229], v[36:39]
	v_mfma_f32_16x16x32_bf16 v[32:35], v[196:199], v[222:225], v[32:35]
	v_mfma_f32_16x16x32_bf16 v[32:35], v[200:203], v[226:229], v[32:35]
	v_mfma_f32_16x16x32_bf16 v[20:23], v[188:191], v[230:233], v[20:23]
	v_mfma_f32_16x16x32_bf16 v[20:23], v[192:195], v[234:237], v[20:23]
	v_mfma_f32_16x16x32_bf16 v[16:19], v[196:199], v[230:233], v[16:19]
	v_mfma_f32_16x16x32_bf16 v[16:19], v[200:203], v[234:237], v[16:19]
	v_mfma_f32_16x16x32_bf16 v[4:7], v[188:191], v[238:241], v[4:7]
	v_mfma_f32_16x16x32_bf16 v[4:7], v[192:195], v[242:245], v[4:7]
	v_mfma_f32_16x16x32_bf16 v[0:3], v[196:199], v[238:241], v[0:3]
	v_mfma_f32_16x16x32_bf16 v[0:3], v[200:203], v[242:245], v[0:3]
	s_barrier
	s_add_i32 s63, s63, 2
	s_add_u32 s70, s70, 0x100
	s_addc_u32 s71, s71, 0
	s_add_u32 s10, s10, 0x100
	s_addc_u32 s61, s61, 0
	s_cmp_gt_u32 s63, 29
	s_cbranch_scc1 .LBB0_435

; #define PG8_STAGE(bufoff, gbase, voff) do { _Pragma("unroll") for (int _i = 0; _i < 2; ++_i) \
;         __builtin_amdgcn_global_load_lds((const unsigned*)((const char*)(gbase) + (voff)[_i]), (PG8_LAS unsigned*)(lds + (bufoff) + ldsw + _i * 8192), 16, 0, 0); } while (0)
; #define PG8_WAIT_V(n) asm volatile("s_waitcnt vmcnt(" #n ")" ::: "memory")
; #define PG8_WAIT_L(n) asm volatile("s_waitcnt lgkmcnt(" #n ")" ::: "memory")
; #define PG8_BAR __builtin_amdgcn_s_barrier()
; #define PG8_SCHED __builtin_amdgcn_sched_barrier(0)
;     ...
;             const bool last = (t == nt - 2);
;             const char* a1 = cA + (size_t)(t + 1) * kstep;
;             const char* a2 = last ? nA : cA + (size_t)(t + 2) * kstep; const char* b2 = last ? nB : cB + (size_t)(t + 2) * kstep;
;             const char* a3 = a2 + kstep; const char* b3 = b2 + kstep;
;             if (last && has_next) S.a_ready(nxt);
;             if (last) E.pre(pre, cur, wr, fr);
;             if constexpr (MIDK > 0) { if (t == MIDK / BK) E.mid(acc, cur, wr, wc, fr, fq); }
;             if constexpr (SP2) {
;             PG8_LDB(B0, 0, 0); PG8_LDB(B1, 0, 1); PG8_SCHED; PG8_LDA(At, 0, 0); PG8_STAGE(PG8_SA(1, 1), a1 + hstep, voffA);
;             PG8_WAIT_V(8); PG8_WAIT_L(0); PG8_BAR; PG8_MMA(0, 0, At, B0); PG8_MMA(0, 1, At, B1); PG8_BAR; PG8_SCHED;
;             PG8_LDA(At, 0, 1); PG8_STAGE(PG8_SB(0, 0), b2, voffB); PG8_STAGE(PG8_SB(0, 1), b2 + hstep, voffB); PG8_STAGE(PG8_SA(0, 0), a2, voffA);
;             PG8_WAIT_V(8); PG8_WAIT_L(0); PG8_BAR; PG8_MMA(1, 0, At, B0); PG8_MMA(1, 1, At, B1); PG8_BAR; PG8_SCHED;
.LBB0_666:
	v_add_u32_e32 v1, s70, v175
	s_add_u32 s33, s52, s54
	ds_read_b128 v[140:143], v1
	ds_read_b128 v[144:147], v1 offset:1024
	ds_read_b128 v[148:151], v1 offset:2048
	ds_read_b128 v[152:155], v1 offset:3072
	v_add_u32_e32 v1, s71, v175
	s_addc_u32 s58, s53, s55
	ds_read_b128 v[190:193], v1
	ds_read_b128 v[194:197], v1 offset:1024
	ds_read_b128 v[198:201], v1 offset:2048
	ds_read_b128 v[202:205], v1 offset:3072
	s_add_u32 s33, s33, 0x100
	s_addc_u32 s76, s58, 0
	s_and_b64 s[58:59], s[56:57], exec
	s_cselect_b32 s59, s34, s76
	s_cselect_b32 s58, s35, s33
	s_add_u32 s33, s73, s54
	s_addc_u32 s76, s74, s55
	s_and_b64 s[56:57], s[56:57], exec
	s_cselect_b32 s57, s45, s76
	s_cselect_b32 s56, s47, s33
	v_lshl_add_u64 v[2:3], v[136:137], 0, s[54:55]
	s_add_i32 m0, s63, 0xc000
	ds_read_b128 v[206:209], v179
	ds_read_b128 v[214:217], v179 offset:1024
	ds_read_b128 v[218:221], v179 offset:2048
	ds_read_b128 v[222:225], v179 offset:3072
	ds_read_b128 v[226:229], v179 offset:4096
	ds_read_b128 v[230:233], v179 offset:5120
	ds_read_b128 v[234:237], v179 offset:6144
	ds_read_b128 v[238:241], v179 offset:7168
	global_load_lds_dwordx4 v[2:3], off
	s_add_i32 m0, s63, 0xe000
	v_lshl_add_u64 v[2:3], v[138:139], 0, s[54:55]
	global_load_lds_dwordx4 v[2:3], off
	s_waitcnt vmcnt(8) lgkmcnt(0)
	s_barrier
	v_mfma_f32_16x16x32_bf16 v[128:131], v[140:143], v[206:209], v[128:131]
	v_mfma_f32_16x16x32_bf16 v[128:131], v[144:147], v[214:217], v[128:131]
	v_mfma_f32_16x16x32_bf16 v[124:127], v[148:151], v[206:209], v[124:127]
	v_mfma_f32_16x16x32_bf16 v[124:127], v[152:155], v[214:217], v[124:127]
	v_mfma_f32_16x16x32_bf16 v[112:115], v[140:143], v[218:221], v[112:115]
	v_mfma_f32_16x16x32_bf16 v[112:115], v[144:147], v[222:225], v[112:115]
	v_mfma_f32_16x16x32_bf16 v[108:111], v[148:151], v[218:221], v[108:111]
	v_mfma_f32_16x16x32_bf16 v[108:111], v[152:155], v[222:225], v[108:111]
	v_mfma_f32_16x16x32_bf16 v[96:99], v[140:143], v[226:229], v[96:99]
	v_mfma_f32_16x16x32_bf16 v[96:99], v[144:147], v[230:233], v[96:99]
	v_mfma_f32_16x16x32_bf16 v[92:95], v[148:151], v[226:229], v[92:95]
	v_mfma_f32_16x16x32_bf16 v[92:95], v[152:155], v[230:233], v[92:95]
	v_mfma_f32_16x16x32_bf16 v[80:83], v[140:143], v[234:237], v[80:83]
	v_mfma_f32_16x16x32_bf16 v[80:83], v[144:147], v[238:241], v[80:83]
	v_mfma_f32_16x16x32_bf16 v[76:79], v[148:151], v[234:237], v[76:79]
	v_mfma_f32_16x16x32_bf16 v[76:79], v[152:155], v[238:241], v[76:79]
	v_mfma_f32_16x16x32_bf16 v[120:123], v[190:193], v[206:209], v[120:123]
	v_mfma_f32_16x16x32_bf16 v[120:123], v[194:197], v[214:217], v[120:123]
	v_mfma_f32_16x16x32_bf16 v[116:119], v[198:201], v[206:209], v[116:119]
	v_mfma_f32_16x16x32_bf16 v[116:119], v[202:205], v[214:217], v[116:119]
	v_mfma_f32_16x16x32_bf16 v[104:107], v[190:193], v[218:221], v[104:107]
	v_mfma_f32_16x16x32_bf16 v[104:107], v[194:197], v[222:225], v[104:107]
	v_mfma_f32_16x16x32_bf16 v[100:103], v[198:201], v[218:221], v[100:103]
	v_mfma_f32_16x16x32_bf16 v[100:103], v[202:205], v[222:225], v[100:103]
	v_mfma_f32_16x16x32_bf16 v[88:91], v[190:193], v[226:229], v[88:91]
	v_mfma_f32_16x16x32_bf16 v[88:91], v[194:197], v[230:233], v[88:91]
	v_mfma_f32_16x16x32_bf16 v[84:87], v[198:201], v[226:229], v[84:87]
	v_mfma_f32_16x16x32_bf16 v[84:87], v[202:205], v[230:233], v[84:87]
	v_mfma_f32_16x16x32_bf16 v[72:75], v[190:193], v[234:237], v[72:75]
	v_mfma_f32_16x16x32_bf16 v[72:75], v[194:197], v[238:241], v[72:75]
	v_mfma_f32_16x16x32_bf16 v[68:71], v[198:201], v[234:237], v[68:71]
	v_mfma_f32_16x16x32_bf16 v[68:71], v[202:205], v[238:241], v[68:71]
	s_barrier
	s_add_i32 s33, s70, s62
	v_lshl_add_u64 v[210:211], s[56:57], 0, v[158:159]
	s_mov_b32 m0, s33
	ds_read_b128 v[206:209], v179 offset:16384
	ds_read_b128 v[214:217], v179 offset:17408
	ds_read_b128 v[218:221], v179 offset:18432
	ds_read_b128 v[222:225], v179 offset:19456
	ds_read_b128 v[226:229], v179 offset:20480
	ds_read_b128 v[230:233], v179 offset:21504
	ds_read_b128 v[234:237], v179 offset:22528
	ds_read_b128 v[238:241], v179 offset:23552
	global_load_lds_dwordx4 v[210:211], off
	s_add_i32 m0, s33, 0x2000
	s_add_u32 s76, s56, 0x80000
	v_lshl_add_u64 v[242:243], s[56:57], 0, v[162:163]
	s_addc_u32 s77, s57, 0
	s_add_i32 s33, s71, s62
	global_load_lds_dwordx4 v[242:243], off
	v_lshl_add_u64 v[2:3], s[76:77], 0, v[158:159]
	s_mov_b32 m0, s33
	v_lshl_add_u64 v[244:245], s[58:59], 0, v[156:157]
	global_load_lds_dwordx4 v[2:3], off
	v_lshl_add_u64 v[2:3], s[76:77], 0, v[162:163]
	s_add_i32 m0, s33, 0x2000
	v_lshl_add_u64 v[246:247], s[58:59], 0, v[160:161]
	global_load_lds_dwordx4 v[2:3], off
	s_mov_b32 m0, s63
	s_nop 0
	global_load_lds_dwordx4 v[244:245], off
	s_mov_b32 m0, s64
	s_nop 0
	global_load_lds_dwordx4 v[246:247], off
	s_waitcnt vmcnt(8) lgkmcnt(0)
	s_barrier
; #define PG8_STAGE(bufoff, gbase, voff) do { _Pragma("unroll") for (int _i = 0; _i < 2; ++_i) \
;         __builtin_amdgcn_global_load_lds((const unsigned*)((const char*)(gbase) + (voff)[_i]), (PG8_LAS unsigned*)(lds + (bufoff) + ldsw + _i * 8192), 16, 0, 0); } while (0)
; #define PG8_WAIT_V(n) asm volatile("s_waitcnt vmcnt(" #n ")" ::: "memory")
; #define PG8_WAIT_L(n) asm volatile("s_waitcnt lgkmcnt(" #n ")" ::: "memory")
; #define PG8_BAR __builtin_amdgcn_s_barrier()
; #define PG8_SCHED __builtin_amdgcn_sched_barrier(0)
;     ...
;             PG8_WAIT_V(8); PG8_WAIT_L(0); PG8_BAR; PG8_MMA(1, 0, At, B0); PG8_MMA(1, 1, At, B1); PG8_BAR; PG8_SCHED;
;             PG8_LDB(B0, 1, 0); PG8_LDB(B1, 1, 1); PG8_SCHED; PG8_LDA(At, 1, 0); PG8_STAGE(PG8_SA(0, 1), a2 + hstep, voffA);
;             PG8_WAIT_V(8); PG8_WAIT_L(0); PG8_BAR; PG8_MMA(0, 0, At, B0); PG8_MMA(0, 1, At, B1); PG8_BAR; PG8_SCHED;
	v_mfma_f32_16x16x32_bf16 v[64:67], v[140:143], v[206:209], v[64:67]
	v_mfma_f32_16x16x32_bf16 v[64:67], v[144:147], v[214:217], v[64:67]
	v_mfma_f32_16x16x32_bf16 v[60:63], v[148:151], v[206:209], v[60:63]
	v_mfma_f32_16x16x32_bf16 v[60:63], v[152:155], v[214:217], v[60:63]
	v_mfma_f32_16x16x32_bf16 v[48:51], v[140:143], v[218:221], v[48:51]
	v_mfma_f32_16x16x32_bf16 v[48:51], v[144:147], v[222:225], v[48:51]
	v_mfma_f32_16x16x32_bf16 v[44:47], v[148:151], v[218:221], v[44:47]
	v_mfma_f32_16x16x32_bf16 v[44:47], v[152:155], v[222:225], v[44:47]
	v_mfma_f32_16x16x32_bf16 v[32:35], v[140:143], v[226:229], v[32:35]
	v_mfma_f32_16x16x32_bf16 v[32:35], v[144:147], v[230:233], v[32:35]
	v_mfma_f32_16x16x32_bf16 v[28:31], v[148:151], v[226:229], v[28:31]
	v_mfma_f32_16x16x32_bf16 v[28:31], v[152:155], v[230:233], v[28:31]
	v_mfma_f32_16x16x32_bf16 v[16:19], v[140:143], v[234:237], v[16:19]
	v_mfma_f32_16x16x32_bf16 v[16:19], v[144:147], v[238:241], v[16:19]
	v_mfma_f32_16x16x32_bf16 v[12:15], v[148:151], v[234:237], v[12:15]
	v_mfma_f32_16x16x32_bf16 v[12:15], v[152:155], v[238:241], v[12:15]
	v_mfma_f32_16x16x32_bf16 v[56:59], v[190:193], v[206:209], v[56:59]
	v_mfma_f32_16x16x32_bf16 v[56:59], v[194:197], v[214:217], v[56:59]
	v_mfma_f32_16x16x32_bf16 v[52:55], v[198:201], v[206:209], v[52:55]
	v_mfma_f32_16x16x32_bf16 v[52:55], v[202:205], v[214:217], v[52:55]
	v_mfma_f32_16x16x32_bf16 v[40:43], v[190:193], v[218:221], v[40:43]
	v_mfma_f32_16x16x32_bf16 v[40:43], v[194:197], v[222:225], v[40:43]
	v_mfma_f32_16x16x32_bf16 v[36:39], v[198:201], v[218:221], v[36:39]
	v_mfma_f32_16x16x32_bf16 v[36:39], v[202:205], v[222:225], v[36:39]
	v_mfma_f32_16x16x32_bf16 v[24:27], v[190:193], v[226:229], v[24:27]
	v_mfma_f32_16x16x32_bf16 v[24:27], v[194:197], v[230:233], v[24:27]
	v_mfma_f32_16x16x32_bf16 v[20:23], v[198:201], v[226:229], v[20:23]
	v_mfma_f32_16x16x32_bf16 v[20:23], v[202:205], v[230:233], v[20:23]
	v_mfma_f32_16x16x32_bf16 v[8:11], v[190:193], v[234:237], v[8:11]
	v_mfma_f32_16x16x32_bf16 v[8:11], v[194:197], v[238:241], v[8:11]
	v_mfma_f32_16x16x32_bf16 v[2:5], v[198:201], v[234:237], v[4:7]
	v_mfma_f32_16x16x32_bf16 v[2:5], v[202:205], v[238:241], v[2:5]
	s_barrier
	s_add_i32 s33, 0, 0x18000
	v_add_u32_e32 v1, s33, v175
	s_add_i32 s76, 0, 0x1c000
	ds_read_b128 v[140:143], v1
	ds_read_b128 v[144:147], v1 offset:1024
	ds_read_b128 v[148:151], v1 offset:2048
	ds_read_b128 v[152:155], v1 offset:3072
	v_add_u32_e32 v1, s76, v175
	ds_read_b128 v[190:193], v1
	ds_read_b128 v[194:197], v1 offset:1024
	ds_read_b128 v[198:201], v1 offset:2048
	ds_read_b128 v[202:205], v1 offset:3072
	s_add_u32 s58, s58, 0x80000
	s_addc_u32 s59, s59, 0
	s_mov_b32 m0, s65
	v_lshl_add_u64 v[6:7], s[58:59], 0, v[156:157]
	ds_read_b128 v[206:209], v179 offset:32768
	ds_read_b128 v[214:217], v179 offset:33792
	ds_read_b128 v[218:221], v179 offset:34816
	ds_read_b128 v[222:225], v179 offset:35840
	ds_read_b128 v[226:229], v179 offset:36864
	ds_read_b128 v[230:233], v179 offset:37888
	ds_read_b128 v[234:237], v179 offset:38912
	ds_read_b128 v[238:241], v179 offset:39936
	global_load_lds_dwordx4 v[6:7], off
	s_mov_b32 m0, s66
	v_lshl_add_u64 v[6:7], s[58:59], 0, v[160:161]
	global_load_lds_dwordx4 v[6:7], off
	s_waitcnt vmcnt(8) lgkmcnt(0)
	s_barrier
	v_mfma_f32_16x16x32_bf16 v[128:131], v[140:143], v[206:209], v[128:131]
	v_mfma_f32_16x16x32_bf16 v[128:131], v[144:147], v[214:217], v[128:131]
	v_mfma_f32_16x16x32_bf16 v[124:127], v[148:151], v[206:209], v[124:127]
	v_mfma_f32_16x16x32_bf16 v[124:127], v[152:155], v[214:217], v[124:127]
	v_mfma_f32_16x16x32_bf16 v[112:115], v[140:143], v[218:221], v[112:115]
	v_mfma_f32_16x16x32_bf16 v[112:115], v[144:147], v[222:225], v[112:115]
	v_mfma_f32_16x16x32_bf16 v[108:111], v[148:151], v[218:221], v[108:111]
	v_mfma_f32_16x16x32_bf16 v[108:111], v[152:155], v[222:225], v[108:111]
	v_mfma_f32_16x16x32_bf16 v[96:99], v[140:143], v[226:229], v[96:99]
	v_mfma_f32_16x16x32_bf16 v[96:99], v[144:147], v[230:233], v[96:99]
	v_mfma_f32_16x16x32_bf16 v[92:95], v[148:151], v[226:229], v[92:95]
	v_mfma_f32_16x16x32_bf16 v[92:95], v[152:155], v[230:233], v[92:95]
	v_mfma_f32_16x16x32_bf16 v[80:83], v[140:143], v[234:237], v[80:83]
	v_mfma_f32_16x16x32_bf16 v[80:83], v[144:147], v[238:241], v[80:83]
	v_mfma_f32_16x16x32_bf16 v[76:79], v[148:151], v[234:237], v[76:79]
	v_mfma_f32_16x16x32_bf16 v[76:79], v[152:155], v[238:241], v[76:79]
	v_mfma_f32_16x16x32_bf16 v[120:123], v[190:193], v[206:209], v[120:123]
	v_mfma_f32_16x16x32_bf16 v[120:123], v[194:197], v[214:217], v[120:123]
	v_mfma_f32_16x16x32_bf16 v[116:119], v[198:201], v[206:209], v[116:119]
	v_mfma_f32_16x16x32_bf16 v[116:119], v[202:205], v[214:217], v[116:119]
	v_mfma_f32_16x16x32_bf16 v[104:107], v[190:193], v[218:221], v[104:107]
	v_mfma_f32_16x16x32_bf16 v[104:107], v[194:197], v[222:225], v[104:107]
	v_mfma_f32_16x16x32_bf16 v[100:103], v[198:201], v[218:221], v[100:103]
	v_mfma_f32_16x16x32_bf16 v[100:103], v[202:205], v[222:225], v[100:103]
	v_mfma_f32_16x16x32_bf16 v[88:91], v[190:193], v[226:229], v[88:91]
	v_mfma_f32_16x16x32_bf16 v[88:91], v[194:197], v[230:233], v[88:91]
	v_mfma_f32_16x16x32_bf16 v[84:87], v[198:201], v[226:229], v[84:87]
	v_mfma_f32_16x16x32_bf16 v[84:87], v[202:205], v[230:233], v[84:87]
	v_mfma_f32_16x16x32_bf16 v[72:75], v[190:193], v[234:237], v[72:75]
	v_mfma_f32_16x16x32_bf16 v[72:75], v[194:197], v[238:241], v[72:75]
	v_mfma_f32_16x16x32_bf16 v[68:71], v[198:201], v[234:237], v[68:71]
	v_mfma_f32_16x16x32_bf16 v[68:71], v[202:205], v[238:241], v[68:71]
	s_barrier
; #define PG8_STAGE(bufoff, gbase, voff) do { _Pragma("unroll") for (int _i = 0; _i < 2; ++_i) \
;         __builtin_amdgcn_global_load_lds((const unsigned*)((const char*)(gbase) + (voff)[_i]), (PG8_LAS unsigned*)(lds + (bufoff) + ldsw + _i * 8192), 16, 0, 0); } while (0)
; #define PG8_WAIT_V(n) asm volatile("s_waitcnt vmcnt(" #n ")" ::: "memory")
; #define PG8_WAIT_L(n) asm volatile("s_waitcnt lgkmcnt(" #n ")" ::: "memory")
; #define PG8_BAR __builtin_amdgcn_s_barrier()
; #define PG8_SCHED __builtin_amdgcn_sched_barrier(0)
;     ...
;             PG8_LDA(At, 1, 1); PG8_STAGE(PG8_SB(1, 0), b3, voffB); PG8_STAGE(PG8_SB(1, 1), b3 + hstep, voffB); PG8_STAGE(PG8_SA(1, 0), a3, voffA);
;             PG8_WAIT_V(8); PG8_WAIT_L(0); PG8_BAR; PG8_MMA(1, 0, At, B0); PG8_MMA(1, 1, At, B1); PG8_BAR; PG8_SCHED;
	s_add_i32 s33, s33, s62
	v_lshl_add_u64 v[6:7], v[210:211], 0, s[40:41]
	s_mov_b32 m0, s33
	ds_read_b128 v[206:209], v179 offset:49152
	ds_read_b128 v[214:217], v179 offset:50176
	ds_read_b128 v[218:221], v179 offset:51200
	ds_read_b128 v[222:225], v179 offset:52224
	ds_read_b128 v[226:229], v179 offset:53248
	ds_read_b128 v[230:233], v179 offset:54272
	ds_read_b128 v[234:237], v179 offset:55296
	ds_read_b128 v[238:241], v179 offset:56320
	global_load_lds_dwordx4 v[6:7], off
	s_add_i32 m0, s33, 0x2000
	s_add_u32 s56, s56, 0x80080
	v_lshl_add_u64 v[6:7], v[242:243], 0, s[40:41]
	s_addc_u32 s57, s57, 0
	s_add_i32 s33, s76, s62
	global_load_lds_dwordx4 v[6:7], off
	s_mov_b32 m0, s33
	v_lshl_add_u64 v[6:7], s[56:57], 0, v[158:159]
	global_load_lds_dwordx4 v[6:7], off
	s_add_i32 m0, s33, 0x2000
	v_lshl_add_u64 v[6:7], s[56:57], 0, v[162:163]
	global_load_lds_dwordx4 v[6:7], off
	s_mov_b32 m0, s68
	v_lshl_add_u64 v[6:7], v[244:245], 0, s[40:41]
	global_load_lds_dwordx4 v[6:7], off
	s_mov_b32 m0, s69
	v_lshl_add_u64 v[6:7], v[246:247], 0, s[40:41]
	global_load_lds_dwordx4 v[6:7], off
	s_waitcnt vmcnt(8) lgkmcnt(0)
	s_barrier
	v_mfma_f32_16x16x32_bf16 v[64:67], v[140:143], v[206:209], v[64:67]
	v_mfma_f32_16x16x32_bf16 v[64:67], v[144:147], v[214:217], v[64:67]
	v_mfma_f32_16x16x32_bf16 v[60:63], v[148:151], v[206:209], v[60:63]
	v_mfma_f32_16x16x32_bf16 v[60:63], v[152:155], v[214:217], v[60:63]
	v_mfma_f32_16x16x32_bf16 v[48:51], v[140:143], v[218:221], v[48:51]
	v_mfma_f32_16x16x32_bf16 v[48:51], v[144:147], v[222:225], v[48:51]
	v_mfma_f32_16x16x32_bf16 v[44:47], v[148:151], v[218:221], v[44:47]
	v_mfma_f32_16x16x32_bf16 v[44:47], v[152:155], v[222:225], v[44:47]
	v_mfma_f32_16x16x32_bf16 v[32:35], v[140:143], v[226:229], v[32:35]
	v_mfma_f32_16x16x32_bf16 v[32:35], v[144:147], v[230:233], v[32:35]
	v_mfma_f32_16x16x32_bf16 v[28:31], v[148:151], v[226:229], v[28:31]
	v_mfma_f32_16x16x32_bf16 v[28:31], v[152:155], v[230:233], v[28:31]
	v_mfma_f32_16x16x32_bf16 v[16:19], v[140:143], v[234:237], v[16:19]
	v_mfma_f32_16x16x32_bf16 v[16:19], v[144:147], v[238:241], v[16:19]
	v_mfma_f32_16x16x32_bf16 v[12:15], v[148:151], v[234:237], v[12:15]
	v_mfma_f32_16x16x32_bf16 v[12:15], v[152:155], v[238:241], v[12:15]
	v_mfma_f32_16x16x32_bf16 v[56:59], v[190:193], v[206:209], v[56:59]
	v_mfma_f32_16x16x32_bf16 v[52:55], v[198:201], v[206:209], v[52:55]
	v_mfma_f32_16x16x32_bf16 v[40:43], v[190:193], v[218:221], v[40:43]
	v_mfma_f32_16x16x32_bf16 v[36:39], v[198:201], v[218:221], v[36:39]
	v_mfma_f32_16x16x32_bf16 v[24:27], v[190:193], v[226:229], v[24:27]
	v_mfma_f32_16x16x32_bf16 v[20:23], v[198:201], v[226:229], v[20:23]
	v_mfma_f32_16x16x32_bf16 v[6:9], v[190:193], v[234:237], v[8:11]
	v_mfma_f32_16x16x32_bf16 v[2:5], v[198:201], v[234:237], v[2:5]
	v_mfma_f32_16x16x32_bf16 v[56:59], v[194:197], v[214:217], v[56:59]
	v_mfma_f32_16x16x32_bf16 v[52:55], v[202:205], v[214:217], v[52:55]
	v_mfma_f32_16x16x32_bf16 v[40:43], v[194:197], v[222:225], v[40:43]
	v_mfma_f32_16x16x32_bf16 v[36:39], v[202:205], v[222:225], v[36:39]
	v_mfma_f32_16x16x32_bf16 v[24:27], v[194:197], v[230:233], v[24:27]
	v_mfma_f32_16x16x32_bf16 v[20:23], v[202:205], v[230:233], v[20:23]
	v_mfma_f32_16x16x32_bf16 v[8:11], v[194:197], v[238:241], v[6:9]
	v_mfma_f32_16x16x32_bf16 v[4:7], v[202:205], v[238:241], v[2:5]
	s_barrier
	s_add_i32 s75, s75, 2
	s_add_u32 s54, s54, 0x100
	s_addc_u32 s55, s55, 0
	s_cmp_gt_u32 s75, 29
	s_cbranch_scc1 .LBB0_671

; #define PG8_STAGE(bufoff, gbase, voff) do { _Pragma("unroll") for (int _i = 0; _i < 2; ++_i) \
;         __builtin_amdgcn_global_load_lds((const unsigned*)((const char*)(gbase) + (voff)[_i]), (PG8_LAS unsigned*)(lds + (bufoff) + ldsw + _i * 8192), 16, 0, 0); } while (0)
; #define PG8_WAIT_V(n) asm volatile("s_waitcnt vmcnt(" #n ")" ::: "memory")
; #define PG8_WAIT_L(n) asm volatile("s_waitcnt lgkmcnt(" #n ")" ::: "memory")
; #define PG8_BAR __builtin_amdgcn_s_barrier()
; #define PG8_SCHED __builtin_amdgcn_sched_barrier(0)
;     ...
;             const bool last = (t == nt - 2);
;             const char* a1 = cA + (size_t)(t + 1) * kstep;
;             const char* a2 = last ? nA : cA + (size_t)(t + 2) * kstep; const char* b2 = last ? nB : cB + (size_t)(t + 2) * kstep;
;             const char* a3 = a2 + kstep; const char* b3 = b2 + kstep;
;             if (last && has_next) S.a_ready(nxt);
;             if (last) E.pre(pre, cur, wr, fr);
;             if constexpr (MIDK > 0) { if (t == MIDK / BK) E.mid(acc, cur, wr, wc, fr, fq); }
;             if constexpr (SP2) {
;             PG8_LDB(B0, 0, 0); PG8_LDB(B1, 0, 1); PG8_SCHED; PG8_LDA(At, 0, 0); PG8_STAGE(PG8_SA(1, 1), a1 + hstep, voffA);
;             PG8_WAIT_V(8); PG8_WAIT_L(0); PG8_BAR; PG8_MMA(0, 0, At, B0); PG8_MMA(0, 1, At, B1); PG8_BAR; PG8_SCHED;
;             PG8_LDA(At, 0, 1); PG8_STAGE(PG8_SB(0, 0), b2, voffB); PG8_STAGE(PG8_SB(0, 1), b2 + hstep, voffB); PG8_STAGE(PG8_SA(0, 0), a2, voffA);
;             PG8_WAIT_V(8); PG8_WAIT_L(0); PG8_BAR; PG8_MMA(1, 0, At, B0); PG8_MMA(1, 1, At, B1); PG8_BAR; PG8_SCHED;
.LBB0_851:
	v_add_u32_e32 v157, s60, v149
	ds_read_b128 v[166:169], v157
	ds_read_b128 v[170:173], v157 offset:1024
	ds_read_b128 v[174:177], v157 offset:2048
	ds_read_b128 v[178:181], v157 offset:3072
	v_add_u32_e32 v157, s61, v149
	ds_read_b128 v[182:185], v157
	ds_read_b128 v[186:189], v157 offset:1024
	ds_read_b128 v[190:193], v157 offset:2048
	ds_read_b128 v[194:197], v157 offset:3072
	s_add_u32 s33, s42, 0xfffc0080
	s_addc_u32 s46, s43, -1
	s_and_b64 s[44:45], s[44:45], exec
	s_cselect_b32 s47, s34, s46
	s_cselect_b32 s46, s35, s33
	s_cselect_b32 s45, s25, s66
	s_cselect_b32 s44, s37, s65
	v_lshl_add_u64 v[210:211], s[42:43], 0, v[138:139]
	s_add_i32 m0, s51, 0xc000
	ds_read_b128 v[198:201], v153
	ds_read_b128 v[202:205], v153 offset:1024
	ds_read_b128 v[206:209], v153 offset:2048
	ds_read_b128 v[214:217], v153 offset:3072
	ds_read_b128 v[218:221], v153 offset:4096
	ds_read_b128 v[222:225], v153 offset:5120
	ds_read_b128 v[226:229], v153 offset:6144
	ds_read_b128 v[230:233], v153 offset:7168
	global_load_lds_dwordx4 v[210:211], off
	s_add_i32 m0, s51, 0xe000
	v_lshl_add_u64 v[210:211], s[42:43], 0, v[140:141]
	global_load_lds_dwordx4 v[210:211], off
	s_waitcnt vmcnt(8) lgkmcnt(0)
	s_barrier
	v_mfma_i32_16x16x64_i8 v[124:127], v[166:169], v[198:201], v[124:127]
	v_mfma_i32_16x16x64_i8 v[124:127], v[170:173], v[202:205], v[124:127]
	v_mfma_i32_16x16x64_i8 v[120:123], v[174:177], v[198:201], v[120:123]
	v_mfma_i32_16x16x64_i8 v[120:123], v[178:181], v[202:205], v[120:123]
	v_mfma_i32_16x16x64_i8 v[108:111], v[166:169], v[206:209], v[108:111]
	v_mfma_i32_16x16x64_i8 v[108:111], v[170:173], v[214:217], v[108:111]
	v_mfma_i32_16x16x64_i8 v[100:103], v[174:177], v[206:209], v[100:103]
	v_mfma_i32_16x16x64_i8 v[100:103], v[178:181], v[214:217], v[100:103]
	v_mfma_i32_16x16x64_i8 v[92:95], v[166:169], v[218:221], v[92:95]
	v_mfma_i32_16x16x64_i8 v[92:95], v[170:173], v[222:225], v[92:95]
	v_mfma_i32_16x16x64_i8 v[84:87], v[174:177], v[218:221], v[84:87]
	v_mfma_i32_16x16x64_i8 v[84:87], v[178:181], v[222:225], v[84:87]
	v_mfma_i32_16x16x64_i8 v[76:79], v[166:169], v[226:229], v[76:79]
	v_mfma_i32_16x16x64_i8 v[76:79], v[170:173], v[230:233], v[76:79]
	v_mfma_i32_16x16x64_i8 v[68:71], v[174:177], v[226:229], v[68:71]
	v_mfma_i32_16x16x64_i8 v[68:71], v[178:181], v[230:233], v[68:71]
	v_mfma_i32_16x16x64_i8 v[116:119], v[182:185], v[198:201], v[116:119]
	v_mfma_i32_16x16x64_i8 v[116:119], v[186:189], v[202:205], v[116:119]
	v_mfma_i32_16x16x64_i8 v[112:115], v[190:193], v[198:201], v[112:115]
	v_mfma_i32_16x16x64_i8 v[112:115], v[194:197], v[202:205], v[112:115]
	v_mfma_i32_16x16x64_i8 v[104:107], v[182:185], v[206:209], v[104:107]
	v_mfma_i32_16x16x64_i8 v[104:107], v[186:189], v[214:217], v[104:107]
	v_mfma_i32_16x16x64_i8 v[96:99], v[190:193], v[206:209], v[96:99]
	v_mfma_i32_16x16x64_i8 v[96:99], v[194:197], v[214:217], v[96:99]
	v_mfma_i32_16x16x64_i8 v[88:91], v[182:185], v[218:221], v[88:91]
	v_mfma_i32_16x16x64_i8 v[88:91], v[186:189], v[222:225], v[88:91]
	v_mfma_i32_16x16x64_i8 v[80:83], v[190:193], v[218:221], v[80:83]
	v_mfma_i32_16x16x64_i8 v[80:83], v[194:197], v[222:225], v[80:83]
	v_mfma_i32_16x16x64_i8 v[72:75], v[182:185], v[226:229], v[72:75]
	v_mfma_i32_16x16x64_i8 v[72:75], v[186:189], v[230:233], v[72:75]
	v_mfma_i32_16x16x64_i8 v[64:67], v[190:193], v[226:229], v[64:67]
	v_mfma_i32_16x16x64_i8 v[64:67], v[194:197], v[230:233], v[64:67]
	s_barrier
	s_add_i32 s33, s60, s48
	v_lshl_add_u64 v[210:211], s[44:45], 0, v[132:133]
	s_mov_b32 m0, s33
	ds_read_b128 v[198:201], v153 offset:16384
	ds_read_b128 v[202:205], v153 offset:17408
	ds_read_b128 v[206:209], v153 offset:18432
	ds_read_b128 v[214:217], v153 offset:19456
	ds_read_b128 v[218:221], v153 offset:20480
	ds_read_b128 v[222:225], v153 offset:21504
	ds_read_b128 v[226:229], v153 offset:22528
	ds_read_b128 v[230:233], v153 offset:23552
	global_load_lds_dwordx4 v[210:211], off
	s_add_i32 m0, s33, 0x2000
	s_add_u32 s68, s44, 0x40000
	v_lshl_add_u64 v[234:235], s[44:45], 0, v[128:129]
	s_addc_u32 s69, s45, 0
	s_add_i32 s33, s61, s48
	global_load_lds_dwordx4 v[234:235], off
	v_lshl_add_u64 v[236:237], s[68:69], 0, v[132:133]
	s_mov_b32 m0, s33
	v_lshl_add_u64 v[238:239], s[46:47], 0, v[130:131]
	global_load_lds_dwordx4 v[236:237], off
	s_add_i32 m0, s33, 0x2000
	v_lshl_add_u64 v[236:237], s[68:69], 0, v[128:129]
	global_load_lds_dwordx4 v[236:237], off
	s_mov_b32 m0, s51
	v_lshl_add_u64 v[236:237], s[46:47], 0, v[134:135]
	global_load_lds_dwordx4 v[236:237], off
	s_mov_b32 m0, s52
	s_nop 0
	global_load_lds_dwordx4 v[238:239], off
	s_waitcnt vmcnt(8) lgkmcnt(0)
	s_barrier
; #define PG8_STAGE(bufoff, gbase, voff) do { _Pragma("unroll") for (int _i = 0; _i < 2; ++_i) \
;         __builtin_amdgcn_global_load_lds((const unsigned*)((const char*)(gbase) + (voff)[_i]), (PG8_LAS unsigned*)(lds + (bufoff) + ldsw + _i * 8192), 16, 0, 0); } while (0)
; #define PG8_WAIT_V(n) asm volatile("s_waitcnt vmcnt(" #n ")" ::: "memory")
; #define PG8_WAIT_L(n) asm volatile("s_waitcnt lgkmcnt(" #n ")" ::: "memory")
; #define PG8_BAR __builtin_amdgcn_s_barrier()
; #define PG8_SCHED __builtin_amdgcn_sched_barrier(0)
;     ...
;             PG8_WAIT_V(8); PG8_WAIT_L(0); PG8_BAR; PG8_MMA(1, 0, At, B0); PG8_MMA(1, 1, At, B1); PG8_BAR; PG8_SCHED;
;             PG8_LDB(B0, 1, 0); PG8_LDB(B1, 1, 1); PG8_SCHED; PG8_LDA(At, 1, 0); PG8_STAGE(PG8_SA(0, 1), a2 + hstep, voffA);
;             PG8_WAIT_V(8); PG8_WAIT_L(0); PG8_BAR; PG8_MMA(0, 0, At, B0); PG8_MMA(0, 1, At, B1); PG8_BAR; PG8_SCHED;
	v_mfma_i32_16x16x64_i8 v[60:63], v[166:169], v[198:201], v[60:63]
	v_mfma_i32_16x16x64_i8 v[60:63], v[170:173], v[202:205], v[60:63]
	v_mfma_i32_16x16x64_i8 v[52:55], v[174:177], v[198:201], v[52:55]
	v_mfma_i32_16x16x64_i8 v[52:55], v[178:181], v[202:205], v[52:55]
	v_mfma_i32_16x16x64_i8 v[44:47], v[166:169], v[206:209], v[44:47]
	v_mfma_i32_16x16x64_i8 v[44:47], v[170:173], v[214:217], v[44:47]
	v_mfma_i32_16x16x64_i8 v[36:39], v[174:177], v[206:209], v[36:39]
	v_mfma_i32_16x16x64_i8 v[36:39], v[178:181], v[214:217], v[36:39]
	v_mfma_i32_16x16x64_i8 v[28:31], v[166:169], v[218:221], v[28:31]
	v_mfma_i32_16x16x64_i8 v[28:31], v[170:173], v[222:225], v[28:31]
	v_mfma_i32_16x16x64_i8 v[20:23], v[174:177], v[218:221], v[20:23]
	v_mfma_i32_16x16x64_i8 v[20:23], v[178:181], v[222:225], v[20:23]
	v_mfma_i32_16x16x64_i8 v[12:15], v[166:169], v[226:229], v[12:15]
	v_mfma_i32_16x16x64_i8 v[12:15], v[170:173], v[230:233], v[12:15]
	v_mfma_i32_16x16x64_i8 v[4:7], v[174:177], v[226:229], v[4:7]
	v_mfma_i32_16x16x64_i8 v[4:7], v[178:181], v[230:233], v[4:7]
	v_mfma_i32_16x16x64_i8 v[56:59], v[182:185], v[198:201], v[56:59]
	v_mfma_i32_16x16x64_i8 v[56:59], v[186:189], v[202:205], v[56:59]
	v_mfma_i32_16x16x64_i8 v[48:51], v[190:193], v[198:201], v[48:51]
	v_mfma_i32_16x16x64_i8 v[48:51], v[194:197], v[202:205], v[48:51]
	v_mfma_i32_16x16x64_i8 v[40:43], v[182:185], v[206:209], v[40:43]
	v_mfma_i32_16x16x64_i8 v[40:43], v[186:189], v[214:217], v[40:43]
	v_mfma_i32_16x16x64_i8 v[32:35], v[190:193], v[206:209], v[32:35]
	v_mfma_i32_16x16x64_i8 v[32:35], v[194:197], v[214:217], v[32:35]
	v_mfma_i32_16x16x64_i8 v[24:27], v[182:185], v[218:221], v[24:27]
	v_mfma_i32_16x16x64_i8 v[24:27], v[186:189], v[222:225], v[24:27]
	v_mfma_i32_16x16x64_i8 v[16:19], v[190:193], v[218:221], v[16:19]
	v_mfma_i32_16x16x64_i8 v[16:19], v[194:197], v[222:225], v[16:19]
	v_mfma_i32_16x16x64_i8 v[8:11], v[182:185], v[226:229], v[8:11]
	v_mfma_i32_16x16x64_i8 v[8:11], v[186:189], v[230:233], v[8:11]
	v_mfma_i32_16x16x64_i8 v[0:3], v[190:193], v[226:229], v[0:3]
	v_mfma_i32_16x16x64_i8 v[0:3], v[194:197], v[230:233], v[0:3]
	s_barrier
	s_add_i32 s33, 0, 0x18000
	v_add_u32_e32 v157, s33, v149
	s_add_i32 s68, 0, 0x1c000
	ds_read_b128 v[166:169], v157
	ds_read_b128 v[170:173], v157 offset:1024
	ds_read_b128 v[174:177], v157 offset:2048
	ds_read_b128 v[178:181], v157 offset:3072
	v_add_u32_e32 v157, s68, v149
	ds_read_b128 v[182:185], v157
	ds_read_b128 v[186:189], v157 offset:1024
	ds_read_b128 v[190:193], v157 offset:2048
	ds_read_b128 v[194:197], v157 offset:3072
	s_add_u32 s46, s46, 0x40000
	s_addc_u32 s47, s47, 0
	s_mov_b32 m0, s53
	v_lshl_add_u64 v[240:241], s[46:47], 0, v[134:135]
	ds_read_b128 v[198:201], v153 offset:32768
	ds_read_b128 v[202:205], v153 offset:33792
	ds_read_b128 v[206:209], v153 offset:34816
	ds_read_b128 v[214:217], v153 offset:35840
	ds_read_b128 v[218:221], v153 offset:36864
	ds_read_b128 v[222:225], v153 offset:37888
	ds_read_b128 v[226:229], v153 offset:38912
	ds_read_b128 v[230:233], v153 offset:39936
	global_load_lds_dwordx4 v[240:241], off
	s_mov_b32 m0, s54
	v_lshl_add_u64 v[240:241], s[46:47], 0, v[130:131]
	global_load_lds_dwordx4 v[240:241], off
	s_waitcnt vmcnt(8) lgkmcnt(0)
	s_barrier
	v_mfma_i32_16x16x64_i8 v[124:127], v[166:169], v[198:201], v[124:127]
	v_mfma_i32_16x16x64_i8 v[124:127], v[170:173], v[202:205], v[124:127]
	v_mfma_i32_16x16x64_i8 v[120:123], v[174:177], v[198:201], v[120:123]
	v_mfma_i32_16x16x64_i8 v[120:123], v[178:181], v[202:205], v[120:123]
	v_mfma_i32_16x16x64_i8 v[108:111], v[166:169], v[206:209], v[108:111]
	v_mfma_i32_16x16x64_i8 v[108:111], v[170:173], v[214:217], v[108:111]
	v_mfma_i32_16x16x64_i8 v[100:103], v[174:177], v[206:209], v[100:103]
	v_mfma_i32_16x16x64_i8 v[100:103], v[178:181], v[214:217], v[100:103]
	v_mfma_i32_16x16x64_i8 v[92:95], v[166:169], v[218:221], v[92:95]
	v_mfma_i32_16x16x64_i8 v[92:95], v[170:173], v[222:225], v[92:95]
	v_mfma_i32_16x16x64_i8 v[84:87], v[174:177], v[218:221], v[84:87]
	v_mfma_i32_16x16x64_i8 v[84:87], v[178:181], v[222:225], v[84:87]
	v_mfma_i32_16x16x64_i8 v[76:79], v[166:169], v[226:229], v[76:79]
	v_mfma_i32_16x16x64_i8 v[76:79], v[170:173], v[230:233], v[76:79]
	v_mfma_i32_16x16x64_i8 v[68:71], v[174:177], v[226:229], v[68:71]
	v_mfma_i32_16x16x64_i8 v[68:71], v[178:181], v[230:233], v[68:71]
	v_mfma_i32_16x16x64_i8 v[116:119], v[182:185], v[198:201], v[116:119]
	v_mfma_i32_16x16x64_i8 v[116:119], v[186:189], v[202:205], v[116:119]
	v_mfma_i32_16x16x64_i8 v[112:115], v[190:193], v[198:201], v[112:115]
	v_mfma_i32_16x16x64_i8 v[112:115], v[194:197], v[202:205], v[112:115]
	v_mfma_i32_16x16x64_i8 v[104:107], v[182:185], v[206:209], v[104:107]
	v_mfma_i32_16x16x64_i8 v[104:107], v[186:189], v[214:217], v[104:107]
	v_mfma_i32_16x16x64_i8 v[96:99], v[190:193], v[206:209], v[96:99]
	v_mfma_i32_16x16x64_i8 v[96:99], v[194:197], v[214:217], v[96:99]
	v_mfma_i32_16x16x64_i8 v[88:91], v[182:185], v[218:221], v[88:91]
	v_mfma_i32_16x16x64_i8 v[88:91], v[186:189], v[222:225], v[88:91]
	v_mfma_i32_16x16x64_i8 v[80:83], v[190:193], v[218:221], v[80:83]
	v_mfma_i32_16x16x64_i8 v[80:83], v[194:197], v[222:225], v[80:83]
	v_mfma_i32_16x16x64_i8 v[72:75], v[182:185], v[226:229], v[72:75]
	v_mfma_i32_16x16x64_i8 v[72:75], v[186:189], v[230:233], v[72:75]
	v_mfma_i32_16x16x64_i8 v[64:67], v[190:193], v[226:229], v[64:67]
	v_mfma_i32_16x16x64_i8 v[64:67], v[194:197], v[230:233], v[64:67]
	s_barrier
; #define PG8_STAGE(bufoff, gbase, voff) do { _Pragma("unroll") for (int _i = 0; _i < 2; ++_i) \
;         __builtin_amdgcn_global_load_lds((const unsigned*)((const char*)(gbase) + (voff)[_i]), (PG8_LAS unsigned*)(lds + (bufoff) + ldsw + _i * 8192), 16, 0, 0); } while (0)
; #define PG8_WAIT_V(n) asm volatile("s_waitcnt vmcnt(" #n ")" ::: "memory")
; #define PG8_WAIT_L(n) asm volatile("s_waitcnt lgkmcnt(" #n ")" ::: "memory")
; #define PG8_BAR __builtin_amdgcn_s_barrier()
; #define PG8_SCHED __builtin_amdgcn_sched_barrier(0)
;     ...
;             PG8_LDA(At, 1, 1); PG8_STAGE(PG8_SB(1, 0), b3, voffB); PG8_STAGE(PG8_SB(1, 1), b3 + hstep, voffB); PG8_STAGE(PG8_SA(1, 0), a3, voffA);
;             PG8_WAIT_V(8); PG8_WAIT_L(0); PG8_BAR; PG8_MMA(1, 0, At, B0); PG8_MMA(1, 1, At, B1); PG8_BAR; PG8_SCHED;
	s_add_i32 s33, s33, s48
	v_lshl_add_u64 v[210:211], v[210:211], 0, s[10:11]
	s_mov_b32 m0, s33
	ds_read_b128 v[198:201], v153 offset:49152
	ds_read_b128 v[202:205], v153 offset:50176
	ds_read_b128 v[206:209], v153 offset:51200
	ds_read_b128 v[214:217], v153 offset:52224
	ds_read_b128 v[218:221], v153 offset:53248
	ds_read_b128 v[222:225], v153 offset:54272
	ds_read_b128 v[226:229], v153 offset:55296
	ds_read_b128 v[230:233], v153 offset:56320
	global_load_lds_dwordx4 v[210:211], off
	s_add_i32 m0, s33, 0x2000
	s_add_u32 s44, s44, 0x40080
	v_lshl_add_u64 v[210:211], v[234:235], 0, s[10:11]
	s_addc_u32 s45, s45, 0
	s_add_i32 s33, s68, s48
	global_load_lds_dwordx4 v[210:211], off
	s_mov_b32 m0, s33
	v_lshl_add_u64 v[210:211], s[44:45], 0, v[132:133]
	global_load_lds_dwordx4 v[210:211], off
	s_add_i32 m0, s33, 0x2000
	v_lshl_add_u64 v[210:211], s[44:45], 0, v[128:129]
	global_load_lds_dwordx4 v[210:211], off
	s_mov_b32 m0, s56
	v_lshl_add_u64 v[210:211], v[236:237], 0, s[10:11]
	global_load_lds_dwordx4 v[210:211], off
	s_mov_b32 m0, s57
	v_lshl_add_u64 v[210:211], v[238:239], 0, s[10:11]
	global_load_lds_dwordx4 v[210:211], off
	s_waitcnt vmcnt(8) lgkmcnt(0)
	s_barrier
	v_mfma_i32_16x16x64_i8 v[60:63], v[166:169], v[198:201], v[60:63]
	v_mfma_i32_16x16x64_i8 v[60:63], v[170:173], v[202:205], v[60:63]
	v_mfma_i32_16x16x64_i8 v[52:55], v[174:177], v[198:201], v[52:55]
	v_mfma_i32_16x16x64_i8 v[52:55], v[178:181], v[202:205], v[52:55]
	v_mfma_i32_16x16x64_i8 v[44:47], v[166:169], v[206:209], v[44:47]
	v_mfma_i32_16x16x64_i8 v[44:47], v[170:173], v[214:217], v[44:47]
	v_mfma_i32_16x16x64_i8 v[36:39], v[174:177], v[206:209], v[36:39]
	v_mfma_i32_16x16x64_i8 v[36:39], v[178:181], v[214:217], v[36:39]
	v_mfma_i32_16x16x64_i8 v[28:31], v[166:169], v[218:221], v[28:31]
	v_mfma_i32_16x16x64_i8 v[28:31], v[170:173], v[222:225], v[28:31]
	v_mfma_i32_16x16x64_i8 v[20:23], v[174:177], v[218:221], v[20:23]
	v_mfma_i32_16x16x64_i8 v[20:23], v[178:181], v[222:225], v[20:23]
	v_mfma_i32_16x16x64_i8 v[12:15], v[166:169], v[226:229], v[12:15]
	v_mfma_i32_16x16x64_i8 v[12:15], v[170:173], v[230:233], v[12:15]
	v_mfma_i32_16x16x64_i8 v[4:7], v[174:177], v[226:229], v[4:7]
	v_mfma_i32_16x16x64_i8 v[4:7], v[178:181], v[230:233], v[4:7]
	v_mfma_i32_16x16x64_i8 v[56:59], v[182:185], v[198:201], v[56:59]
	v_mfma_i32_16x16x64_i8 v[56:59], v[186:189], v[202:205], v[56:59]
	v_mfma_i32_16x16x64_i8 v[48:51], v[190:193], v[198:201], v[48:51]
	v_mfma_i32_16x16x64_i8 v[48:51], v[194:197], v[202:205], v[48:51]
	v_mfma_i32_16x16x64_i8 v[40:43], v[182:185], v[206:209], v[40:43]
	v_mfma_i32_16x16x64_i8 v[40:43], v[186:189], v[214:217], v[40:43]
	v_mfma_i32_16x16x64_i8 v[32:35], v[190:193], v[206:209], v[32:35]
	v_mfma_i32_16x16x64_i8 v[32:35], v[194:197], v[214:217], v[32:35]
	v_mfma_i32_16x16x64_i8 v[24:27], v[182:185], v[218:221], v[24:27]
	v_mfma_i32_16x16x64_i8 v[24:27], v[186:189], v[222:225], v[24:27]
	v_mfma_i32_16x16x64_i8 v[16:19], v[190:193], v[218:221], v[16:19]
	v_mfma_i32_16x16x64_i8 v[16:19], v[194:197], v[222:225], v[16:19]
	v_mfma_i32_16x16x64_i8 v[8:11], v[182:185], v[226:229], v[8:11]
	v_mfma_i32_16x16x64_i8 v[8:11], v[186:189], v[230:233], v[8:11]
	v_mfma_i32_16x16x64_i8 v[0:3], v[190:193], v[226:229], v[0:3]
	v_mfma_i32_16x16x64_i8 v[0:3], v[194:197], v[230:233], v[0:3]
	s_barrier
	s_add_i32 s67, s67, 2
	s_add_u32 s42, s42, 0x100
	s_addc_u32 s43, s43, 0
	s_add_u32 s65, s65, 0x100
	s_addc_u32 s66, s66, 0
	s_cmp_gt_u32 s67, 13
	s_cbranch_scc1 .LBB0_854

; #define PG8_STAGE(bufoff, gbase, voff) do { _Pragma("unroll") for (int _i = 0; _i < 2; ++_i) \
;         __builtin_amdgcn_global_load_lds((const unsigned*)((const char*)(gbase) + (voff)[_i]), (PG8_LAS unsigned*)(lds + (bufoff) + ldsw + _i * 8192), 16, 0, 0); } while (0)
; #define PG8_WAIT_V(n) asm volatile("s_waitcnt vmcnt(" #n ")" ::: "memory")
; #define PG8_WAIT_L(n) asm volatile("s_waitcnt lgkmcnt(" #n ")" ::: "memory")
; #define PG8_BAR __builtin_amdgcn_s_barrier()
; #define PG8_SCHED __builtin_amdgcn_sched_barrier(0)
;     ...
;             const bool last = (t == nt - 2);
;             const char* a1 = cA + (size_t)(t + 1) * kstep;
;             const char* a2 = last ? nA : cA + (size_t)(t + 2) * kstep; const char* b2 = last ? nB : cB + (size_t)(t + 2) * kstep;
;             const char* a3 = a2 + kstep; const char* b3 = b2 + kstep;
;             if (last && has_next) S.a_ready(nxt);
;             if (last) E.pre(pre, cur, wr, fr);
;             if constexpr (MIDK > 0) { if (t == MIDK / BK) E.mid(acc, cur, wr, wc, fr, fq); }
;             if constexpr (SP2) {
;             PG8_LDB(B0, 0, 0); PG8_LDB(B1, 0, 1); PG8_SCHED; PG8_LDA(At, 0, 0); PG8_STAGE(PG8_SA(1, 1), a1 + hstep, voffA);
;             PG8_WAIT_V(8); PG8_WAIT_L(0); PG8_BAR; PG8_MMA(0, 0, At, B0); PG8_MMA(0, 1, At, B1); PG8_BAR; PG8_SCHED;
;             PG8_LDA(At, 0, 1); PG8_STAGE(PG8_SB(0, 0), b2, voffB); PG8_STAGE(PG8_SB(0, 1), b2 + hstep, voffB); PG8_STAGE(PG8_SA(0, 0), a2, voffA);
;             PG8_WAIT_V(8); PG8_WAIT_L(0); PG8_BAR; PG8_MMA(1, 0, At, B0); PG8_MMA(1, 1, At, B1); PG8_BAR; PG8_SCHED;
.LBB0_936:
	ds_read_b128 v[16:19], v187
	ds_read_b128 v[20:23], v187 offset:16
	ds_read_b128 v[24:27], v187 offset:2048
	ds_read_b128 v[28:31], v187 offset:2064
	ds_read_b128 v[0:3], v188
	ds_read_b128 v[4:7], v188 offset:16
	ds_read_b128 v[8:11], v188 offset:2048
	ds_read_b128 v[12:15], v188 offset:2064
	s_add_u32 s24, s20, 0xfff50080
	s_addc_u32 s25, s21, -1
	s_cmp_eq_u32 s48, 40
	s_cselect_b32 s29, s5, s25
	s_cselect_b32 s28, s4, s24
	s_cselect_b32 s25, s19, s47
	s_cselect_b32 s24, s18, s46
	v_lshl_add_u64 v[214:215], s[20:21], 0, v[168:169]
	s_add_i32 m0, s31, 0xc000
	ds_read_b128 v[176:179], v189
	ds_read_b128 v[180:183], v189 offset:16
	ds_read_b128 v[190:193], v189 offset:2048
	ds_read_b128 v[194:197], v189 offset:2064
	ds_read_b128 v[198:201], v189 offset:4096
	ds_read_b128 v[202:205], v189 offset:4112
	ds_read_b128 v[206:209], v189 offset:6144
	ds_read_b128 v[210:213], v189 offset:6160
	global_load_lds_dwordx4 v[214:215], off
	s_add_i32 m0, s31, 0xe000
	v_lshl_add_u64 v[214:215], s[20:21], 0, v[170:171]
	global_load_lds_dwordx4 v[214:215], off
	s_waitcnt vmcnt(8) lgkmcnt(0)
	s_barrier
	v_mfma_f32_16x16x128_f8f6f4 v[156:159], v[16:23], v[176:183], v[156:159]
	v_mfma_f32_16x16x128_f8f6f4 v[152:155], v[24:31], v[176:183], v[152:155]
	v_mfma_f32_16x16x128_f8f6f4 v[148:151], v[16:23], v[190:197], v[148:151]
	v_mfma_f32_16x16x128_f8f6f4 v[144:147], v[24:31], v[190:197], v[144:147]
	v_mfma_f32_16x16x128_f8f6f4 v[128:131], v[16:23], v[198:205], v[128:131]
	v_mfma_f32_16x16x128_f8f6f4 v[120:123], v[24:31], v[198:205], v[120:123]
	v_mfma_f32_16x16x128_f8f6f4 v[112:115], v[16:23], v[206:213], v[112:115]
	v_mfma_f32_16x16x128_f8f6f4 v[104:107], v[24:31], v[206:213], v[104:107]
	v_mfma_f32_16x16x128_f8f6f4 v[140:143], v[0:7], v[176:183], v[140:143]
	v_mfma_f32_16x16x128_f8f6f4 v[136:139], v[8:15], v[176:183], v[136:139]
	v_mfma_f32_16x16x128_f8f6f4 v[132:135], v[0:7], v[190:197], v[132:135]
	v_mfma_f32_16x16x128_f8f6f4 v[124:127], v[8:15], v[190:197], v[124:127]
	v_mfma_f32_16x16x128_f8f6f4 v[116:119], v[0:7], v[198:205], v[116:119]
	v_mfma_f32_16x16x128_f8f6f4 v[108:111], v[8:15], v[198:205], v[108:111]
	v_mfma_f32_16x16x128_f8f6f4 v[100:103], v[0:7], v[206:213], v[100:103]
	v_mfma_f32_16x16x128_f8f6f4 v[96:99], v[8:15], v[206:213], v[96:99]
	s_barrier
	s_add_i32 s49, s40, s30
	v_lshl_add_u64 v[176:177], s[24:25], 0, v[162:163]
	s_mov_b32 m0, s49
	ds_read_b128 v[190:193], v189 offset:16384
	ds_read_b128 v[194:197], v189 offset:16400
	ds_read_b128 v[198:201], v189 offset:18432
	ds_read_b128 v[202:205], v189 offset:18448
	ds_read_b128 v[206:209], v189 offset:20480
	ds_read_b128 v[210:213], v189 offset:20496
	ds_read_b128 v[214:217], v189 offset:22528
	ds_read_b128 v[218:221], v189 offset:22544
	global_load_lds_dwordx4 v[176:177], off
	s_add_i32 m0, s49, 0x2000
	s_add_u32 s50, s24, 0xb0000
	v_lshl_add_u64 v[178:179], s[24:25], 0, v[166:167]
	s_addc_u32 s51, s25, 0
	s_add_i32 s49, s41, s30
	global_load_lds_dwordx4 v[178:179], off
	v_lshl_add_u64 v[180:181], s[50:51], 0, v[162:163]
	s_mov_b32 m0, s49
	v_lshl_add_u64 v[182:183], s[28:29], 0, v[164:165]
	global_load_lds_dwordx4 v[180:181], off
	s_add_i32 m0, s49, 0x2000
	v_lshl_add_u64 v[180:181], s[50:51], 0, v[166:167]
	global_load_lds_dwordx4 v[180:181], off
	s_mov_b32 m0, s31
	v_lshl_add_u64 v[180:181], s[28:29], 0, v[160:161]
	global_load_lds_dwordx4 v[180:181], off
	s_mov_b32 m0, s33
	s_nop 0
	global_load_lds_dwordx4 v[182:183], off
	s_waitcnt vmcnt(8) lgkmcnt(0)
	s_barrier
	v_mfma_f32_16x16x128_f8f6f4 v[92:95], v[16:23], v[190:197], v[92:95]
	v_mfma_f32_16x16x128_f8f6f4 v[88:91], v[24:31], v[190:197], v[88:91]
	v_mfma_f32_16x16x128_f8f6f4 v[80:83], v[16:23], v[198:205], v[80:83]
	v_mfma_f32_16x16x128_f8f6f4 v[72:75], v[24:31], v[198:205], v[72:75]
	v_mfma_f32_16x16x128_f8f6f4 v[64:67], v[16:23], v[206:213], v[64:67]
	v_mfma_f32_16x16x128_f8f6f4 v[56:59], v[24:31], v[206:213], v[56:59]
	v_mfma_f32_16x16x128_f8f6f4 v[48:51], v[16:23], v[214:221], v[48:51]
	v_mfma_f32_16x16x128_f8f6f4 v[40:43], v[24:31], v[214:221], v[40:43]
	v_mfma_f32_16x16x128_f8f6f4 v[84:87], v[0:7], v[190:197], v[84:87]
	v_mfma_f32_16x16x128_f8f6f4 v[76:79], v[8:15], v[190:197], v[76:79]
	v_mfma_f32_16x16x128_f8f6f4 v[68:71], v[0:7], v[198:205], v[68:71]
	v_mfma_f32_16x16x128_f8f6f4 v[60:63], v[8:15], v[198:205], v[60:63]
	v_mfma_f32_16x16x128_f8f6f4 v[52:55], v[0:7], v[206:213], v[52:55]
	v_mfma_f32_16x16x128_f8f6f4 v[44:47], v[8:15], v[206:213], v[44:47]
	v_mfma_f32_16x16x128_f8f6f4 v[36:39], v[0:7], v[214:221], v[36:39]
	v_mfma_f32_16x16x128_f8f6f4 v[32:35], v[8:15], v[214:221], v[32:35]
	s_barrier
; #define PG8_STAGE(bufoff, gbase, voff) do { _Pragma("unroll") for (int _i = 0; _i < 2; ++_i) \
;         __builtin_amdgcn_global_load_lds((const unsigned*)((const char*)(gbase) + (voff)[_i]), (PG8_LAS unsigned*)(lds + (bufoff) + ldsw + _i * 8192), 16, 0, 0); } while (0)
; #define PG8_WAIT_V(n) asm volatile("s_waitcnt vmcnt(" #n ")" ::: "memory")
; #define PG8_WAIT_L(n) asm volatile("s_waitcnt lgkmcnt(" #n ")" ::: "memory")
; #define PG8_BAR __builtin_amdgcn_s_barrier()
; #define PG8_SCHED __builtin_amdgcn_sched_barrier(0)
;     ...
;             PG8_LDB(B0, 1, 0); PG8_LDB(B1, 1, 1); PG8_SCHED; PG8_LDA(At, 1, 0); PG8_STAGE(PG8_SA(0, 1), a2 + hstep, voffA);
;             PG8_WAIT_V(8); PG8_WAIT_L(0); PG8_BAR; PG8_MMA(0, 0, At, B0); PG8_MMA(0, 1, At, B1); PG8_BAR; PG8_SCHED;
;             PG8_LDA(At, 1, 1); PG8_STAGE(PG8_SB(1, 0), b3, voffB); PG8_STAGE(PG8_SB(1, 1), b3 + hstep, voffB); PG8_STAGE(PG8_SA(1, 0), a3, voffA);
;             PG8_WAIT_V(8); PG8_WAIT_L(0); PG8_BAR; PG8_MMA(1, 0, At, B0); PG8_MMA(1, 1, At, B1); PG8_BAR; PG8_SCHED;
;     ...
;         if constexpr (F8) asm volatile("s_nop 15\n\ts_nop 15" ::: "memory");
;         if constexpr (ALIGN_EPI) { if (wr == 0) PG8_BAR; }
	s_add_i32 s49, 0, 0x18000
	s_add_i32 s50, 0, 0x1c000
	v_add_u32_e32 v12, s49, v185
	v_add_u32_e32 v28, s50, v185
	ds_read_b128 v[0:3], v12
	ds_read_b128 v[4:7], v12 offset:16
	ds_read_b128 v[8:11], v12 offset:2048
	ds_read_b128 v[12:15], v12 offset:2064
	ds_read_b128 v[16:19], v28
	ds_read_b128 v[20:23], v28 offset:16
	ds_read_b128 v[24:27], v28 offset:2048
	ds_read_b128 v[28:31], v28 offset:2064
	s_add_u32 s28, s28, 0xb0000
	s_addc_u32 s29, s29, 0
	s_mov_b32 m0, s34
	v_lshl_add_u64 v[222:223], s[28:29], 0, v[160:161]
	ds_read_b128 v[190:193], v189 offset:32768
	ds_read_b128 v[194:197], v189 offset:32784
	ds_read_b128 v[198:201], v189 offset:34816
	ds_read_b128 v[202:205], v189 offset:34832
	ds_read_b128 v[206:209], v189 offset:36864
	ds_read_b128 v[210:213], v189 offset:36880
	ds_read_b128 v[214:217], v189 offset:38912
	ds_read_b128 v[218:221], v189 offset:38928
	global_load_lds_dwordx4 v[222:223], off
	s_mov_b32 m0, s35
	v_lshl_add_u64 v[222:223], s[28:29], 0, v[164:165]
	global_load_lds_dwordx4 v[222:223], off
	s_waitcnt vmcnt(8) lgkmcnt(0)
	s_barrier
	v_mfma_f32_16x16x128_f8f6f4 v[156:159], v[0:7], v[190:197], v[156:159]
	v_mfma_f32_16x16x128_f8f6f4 v[152:155], v[8:15], v[190:197], v[152:155]
	v_mfma_f32_16x16x128_f8f6f4 v[148:151], v[0:7], v[198:205], v[148:151]
	v_mfma_f32_16x16x128_f8f6f4 v[144:147], v[8:15], v[198:205], v[144:147]
	v_mfma_f32_16x16x128_f8f6f4 v[128:131], v[0:7], v[206:213], v[128:131]
	v_mfma_f32_16x16x128_f8f6f4 v[120:123], v[8:15], v[206:213], v[120:123]
	v_mfma_f32_16x16x128_f8f6f4 v[112:115], v[0:7], v[214:221], v[112:115]
	v_mfma_f32_16x16x128_f8f6f4 v[104:107], v[8:15], v[214:221], v[104:107]
	v_mfma_f32_16x16x128_f8f6f4 v[140:143], v[16:23], v[190:197], v[140:143]
	v_mfma_f32_16x16x128_f8f6f4 v[136:139], v[24:31], v[190:197], v[136:139]
	v_mfma_f32_16x16x128_f8f6f4 v[132:135], v[16:23], v[198:205], v[132:135]
	v_mfma_f32_16x16x128_f8f6f4 v[124:127], v[24:31], v[198:205], v[124:127]
	v_mfma_f32_16x16x128_f8f6f4 v[116:119], v[16:23], v[206:213], v[116:119]
	v_mfma_f32_16x16x128_f8f6f4 v[108:111], v[24:31], v[206:213], v[108:111]
	v_mfma_f32_16x16x128_f8f6f4 v[100:103], v[16:23], v[214:221], v[100:103]
	v_mfma_f32_16x16x128_f8f6f4 v[96:99], v[24:31], v[214:221], v[96:99]
	s_barrier
	s_add_i32 s28, s49, s30
	v_lshl_add_u64 v[176:177], v[176:177], 0, s[8:9]
	s_mov_b32 m0, s28
	ds_read_b128 v[190:193], v189 offset:49152
	ds_read_b128 v[194:197], v189 offset:49168
	ds_read_b128 v[198:201], v189 offset:51200
	ds_read_b128 v[202:205], v189 offset:51216
	ds_read_b128 v[206:209], v189 offset:53248
	ds_read_b128 v[210:213], v189 offset:53264
	ds_read_b128 v[214:217], v189 offset:55296
	ds_read_b128 v[218:221], v189 offset:55312
	global_load_lds_dwordx4 v[176:177], off
	s_add_i32 m0, s28, 0x2000
	s_add_u32 s24, s24, 0xb0080
	v_lshl_add_u64 v[176:177], v[178:179], 0, s[8:9]
	s_addc_u32 s25, s25, 0
	s_add_i32 s28, s50, s30
	global_load_lds_dwordx4 v[176:177], off
	s_mov_b32 m0, s28
	v_lshl_add_u64 v[176:177], s[24:25], 0, v[162:163]
	global_load_lds_dwordx4 v[176:177], off
	s_add_i32 m0, s28, 0x2000
	v_lshl_add_u64 v[176:177], s[24:25], 0, v[166:167]
	global_load_lds_dwordx4 v[176:177], off
	s_mov_b32 m0, s37
	v_lshl_add_u64 v[176:177], v[180:181], 0, s[8:9]
	global_load_lds_dwordx4 v[176:177], off
	s_mov_b32 m0, s38
	v_lshl_add_u64 v[176:177], v[182:183], 0, s[8:9]
	global_load_lds_dwordx4 v[176:177], off
	s_waitcnt vmcnt(8) lgkmcnt(0)
	s_barrier
	v_mfma_f32_16x16x128_f8f6f4 v[92:95], v[0:7], v[190:197], v[92:95]
	v_mfma_f32_16x16x128_f8f6f4 v[88:91], v[8:15], v[190:197], v[88:91]
	v_mfma_f32_16x16x128_f8f6f4 v[80:83], v[0:7], v[198:205], v[80:83]
	v_mfma_f32_16x16x128_f8f6f4 v[72:75], v[8:15], v[198:205], v[72:75]
	v_mfma_f32_16x16x128_f8f6f4 v[64:67], v[0:7], v[206:213], v[64:67]
	v_mfma_f32_16x16x128_f8f6f4 v[56:59], v[8:15], v[206:213], v[56:59]
	v_mfma_f32_16x16x128_f8f6f4 v[48:51], v[0:7], v[214:221], v[48:51]
	v_mfma_f32_16x16x128_f8f6f4 v[40:43], v[8:15], v[214:221], v[40:43]
	v_mfma_f32_16x16x128_f8f6f4 v[84:87], v[16:23], v[190:197], v[84:87]
	v_mfma_f32_16x16x128_f8f6f4 v[76:79], v[24:31], v[190:197], v[76:79]
	v_mfma_f32_16x16x128_f8f6f4 v[68:71], v[16:23], v[198:205], v[68:71]
	v_mfma_f32_16x16x128_f8f6f4 v[60:63], v[24:31], v[198:205], v[60:63]
	v_mfma_f32_16x16x128_f8f6f4 v[52:55], v[16:23], v[206:213], v[52:55]
	v_mfma_f32_16x16x128_f8f6f4 v[44:47], v[24:31], v[206:213], v[44:47]
	v_mfma_f32_16x16x128_f8f6f4 v[36:39], v[16:23], v[214:221], v[36:39]
	v_mfma_f32_16x16x128_f8f6f4 v[32:35], v[24:31], v[214:221], v[32:35]
	s_barrier
	s_add_i32 s48, s48, 2
	s_add_u32 s20, s20, 0x100
	s_addc_u32 s21, s21, 0
	s_add_u32 s46, s46, 0x100
	s_addc_u32 s47, s47, 0
	s_cmp_gt_u32 s48, 41
	s_cbranch_scc0 .LBB0_936
	s_nop 15
	s_nop 15
	s_and_b64 vcc, exec, s[10:11]
	s_cbranch_vccz .LBB0_939
	s_barrier
